# MLA: second max chain interleaved with the PV MFMAs on top of the late tile loads
# baseline (speedup 1.0000x reference)
; __device__ __forceinline__ void finishSM9(f32x16& p0, f32x16& p1, float alpha, float& l_reg, v8i32& p8) {
; #pragma unroll
;   for (int r = 0; r < 16; ++r) { p0[r] = __builtin_amdgcn_exp2f(p0[r]); p1[r] = __builtin_amdgcn_exp2f(p1[r]); }
;   float ps = 0;
; #pragma unroll
;   for (int r = 0; r < 16; ++r) ps += p0[r];
; #pragma unroll
;   for (int r = 0; r < 16; ++r) ps += p1[r];
;   { auto rr = __builtin_amdgcn_permlane32_swap(__float_as_uint(ps), __float_as_uint(ps), false, false);
;     ps = __uint_as_float(rr[0]) + __uint_as_float(rr[1]); }
;   l_reg = l_reg * alpha + ps;
; #pragma unroll
;   for (int g = 0; g < 4; ++g) {
;     int w = __builtin_amdgcn_cvt_pk_fp8_f32(p0[4 * g], p0[4 * g + 1], 0, false); p8[g] = __builtin_amdgcn_cvt_pk_fp8_f32(p0[4 * g + 2], p0[4 * g + 3], w, true);
;     int u = __builtin_amdgcn_cvt_pk_fp8_f32(p1[4 * g], p1[4 * g + 1], 0, false); p8[4 + g] = __builtin_amdgcn_cvt_pk_fp8_f32(p1[4 * g + 2], p1[4 * g + 3], u, true); }
; }
; __device__ __forceinline__ void pv8(f32x16* o, const char* Vt, const v8i32 p8, int r32, int hi) {
;   const int sw = (r32 >> 2) & 3, a0 = r32 * 64 + (((hi * 2) ^ sw) << 4), a1 = r32 * 64 + (((hi * 2 + 1) ^ sw) << 4);
; #pragma unroll
;   for (int d0 = 0; d0 < 4; ++d0) {
;     const v8i32 vf = cat8(*reinterpret_cast<const v4i32*>(Vt + d0 * 2048 + a0), *reinterpret_cast<const v4i32*>(Vt + d0 * 2048 + a1));
;     o[d0] = __builtin_amdgcn_mfma_scale_f32_32x32x64_f8f6f4(p8, vf, o[d0], 0, 0, 0, 127, 0, 127); }
; }
; __device__ __forceinline__ void qkt9(f32x16& p0, f32x16& p1, const char* Kn, const char* Kr, const v8i32* qf, const float init, int r32, int hi) {
; #pragma unroll
;   for (int r = 0; r < 16; ++r) { p0[r] = init; p1[r] = init; }
; #pragma unroll
;   for (int s = 0; s < 2; ++s) { const int c0 = s * 4 + hi * 2;
;     const v8i32 a0 = cat8(*reinterpret_cast<const v4i32*>(Kn + KN8SW(r32, c0)), *reinterpret_cast<const v4i32*>(Kn + KN8SW(r32, c0 + 1)));
;     const v8i32 a1 = cat8(*reinterpret_cast<const v4i32*>(Kn + 4096 + KN8SW(r32, c0)), *reinterpret_cast<const v4i32*>(Kn + 4096 + KN8SW(r32, c0 + 1)));
;     p0 = __builtin_amdgcn_mfma_scale_f32_32x32x64_f8f6f4(a0, qf[s], p0, 0, 0, 0, 127, 0, 124);
;     p1 = __builtin_amdgcn_mfma_scale_f32_32x32x64_f8f6f4(a1, qf[s], p1, 0, 0, 0, 127, 0, 124); }
;   { const int c0 = hi * 2;
.LBB0_1321:
	ds_read_b128 v[114:117], v215 offset:24576
	ds_read_b128 v[118:121], v216 offset:24576
	ds_read_b128 v[222:225], v215 offset:28672
	ds_read_b128 v[226:229], v216 offset:28672
	global_load_dwordx4 v[158:161], v176, s[18:19]
	global_load_dwordx4 v[162:165], v178, s[16:17]
	global_load_dwordx4 v[154:157], v[180:181], off
	v_exp_f32_e32 v0, v82
	v_exp_f32_e32 v177, v83
	v_exp_f32_e32 v179, v84
	v_exp_f32_e32 v254, v85
	v_add_f32_e32 v219, v0, v177
	v_cvt_pk_fp8_f32 v246, v0, v177
	v_add_f32_e32 v219, v179, v219
	v_add_f32_e32 v219, v254, v219
	v_cvt_pk_fp8_f32 v246, v179, v254 op_sel:[0,0,1]
	s_waitcnt lgkmcnt(2)
	v_mfma_scale_f32_32x32x64_f8f6f4 v[114:129], v[114:121], v[146:153], v[230:245], v194, v193 op_sel_hi:[0,0,0]
	v_exp_f32_e32 v0, v86
	v_exp_f32_e32 v177, v87
	v_exp_f32_e32 v179, v88
	v_exp_f32_e32 v254, v89
	v_add_f32_e32 v219, v0, v219
	v_add_f32_e32 v219, v177, v219
	v_cvt_pk_fp8_f32 v247, v0, v177
	v_add_f32_e32 v219, v179, v219
	v_add_f32_e32 v219, v254, v219
	v_cvt_pk_fp8_f32 v247, v179, v254 op_sel:[0,0,1]
	ds_read_b128 v[82:85], v213 offset:24576
	ds_read_b128 v[86:89], v214 offset:24576
	s_waitcnt lgkmcnt(2)
	v_mfma_scale_f32_32x32x64_f8f6f4 v[98:113], v[222:229], v[146:153], v[230:245], v194, v193 op_sel_hi:[0,0,0]
	ds_read_b128 v[222:225], v213 offset:28672
	ds_read_b128 v[226:229], v214 offset:28672
	v_exp_f32_e32 v0, v90
	v_exp_f32_e32 v177, v91
	v_exp_f32_e32 v179, v92
	v_exp_f32_e32 v254, v93
	v_add_f32_e32 v219, v0, v219
	v_add_f32_e32 v219, v177, v219
	v_cvt_pk_fp8_f32 v248, v0, v177
	v_add_f32_e32 v219, v179, v219
	v_add_f32_e32 v219, v254, v219
	v_cvt_pk_fp8_f32 v248, v179, v254 op_sel:[0,0,1]
	v_exp_f32_e32 v0, v94
	v_exp_f32_e32 v177, v95
	v_exp_f32_e32 v179, v96
	v_exp_f32_e32 v254, v97
	v_add_f32_e32 v219, v0, v219
	v_add_f32_e32 v219, v177, v219
	v_cvt_pk_fp8_f32 v249, v0, v177
	v_add_f32_e32 v219, v179, v219
	v_add_f32_e32 v219, v254, v219
	v_cvt_pk_fp8_f32 v249, v179, v254 op_sel:[0,0,1]
	ds_read_b128 v[90:93], v185 offset:36864
	ds_read_b128 v[94:97], v186 offset:36864
	s_waitcnt lgkmcnt(4)
	v_mfma_scale_f32_32x32x64_f8f6f4 v[114:129], v[82:89], v[138:145], v[114:129], v194, v193 op_sel_hi:[0,0,0]
	v_exp_f32_e32 v0, v66
	v_exp_f32_e32 v177, v67
	v_exp_f32_e32 v179, v68
	v_exp_f32_e32 v254, v69
	v_add_f32_e32 v219, v0, v219
	v_add_f32_e32 v219, v177, v219
	v_cvt_pk_fp8_f32 v250, v0, v177
	v_add_f32_e32 v219, v179, v219
	v_add_f32_e32 v219, v254, v219
	v_cvt_pk_fp8_f32 v250, v179, v254 op_sel:[0,0,1]
	s_waitcnt lgkmcnt(2)
	v_mfma_scale_f32_32x32x64_f8f6f4 v[98:113], v[222:229], v[138:145], v[98:113], v194, v193 op_sel_hi:[0,0,0]
	ds_read_b128 v[222:225], v185 offset:38912
	ds_read_b128 v[226:229], v186 offset:38912
	v_exp_f32_e32 v0, v70
	v_exp_f32_e32 v177, v71
	v_exp_f32_e32 v179, v72
	v_exp_f32_e32 v254, v73
	v_add_f32_e32 v219, v0, v219
	v_add_f32_e32 v219, v177, v219
	v_cvt_pk_fp8_f32 v251, v0, v177
	v_add_f32_e32 v219, v179, v219
	v_add_f32_e32 v219, v254, v219
	v_cvt_pk_fp8_f32 v251, v179, v254 op_sel:[0,0,1]
	v_exp_f32_e32 v0, v74
	v_exp_f32_e32 v177, v75
	v_exp_f32_e32 v179, v76
	v_exp_f32_e32 v254, v77
	v_add_f32_e32 v219, v0, v219
	v_add_f32_e32 v219, v177, v219
	v_cvt_pk_fp8_f32 v252, v0, v177
	v_add_f32_e32 v219, v179, v219
	v_add_f32_e32 v219, v254, v219
	v_cvt_pk_fp8_f32 v252, v179, v254 op_sel:[0,0,1]
	s_waitcnt lgkmcnt(2)
	v_mfma_scale_f32_32x32x64_f8f6f4 v[114:129], v[90:97], v[130:137], v[114:129], v194, v193 op_sel_hi:[0,0,0]
	v_exp_f32_e32 v0, v78
	v_exp_f32_e32 v177, v79
	v_exp_f32_e32 v179, v80
	v_exp_f32_e32 v254, v81
	v_add_f32_e32 v219, v0, v219
	v_add_f32_e32 v219, v177, v219
	v_cvt_pk_fp8_f32 v253, v0, v177
	v_add_f32_e32 v219, v179, v219
	v_add_f32_e32 v219, v254, v219
	v_cvt_pk_fp8_f32 v253, v179, v254 op_sel:[0,0,1]
	ds_read_b128 v[90:93], v185 offset:0
	ds_read_b128 v[94:97], v186 offset:0
	ds_read_b128 v[82:85], v185 offset:2048
	ds_read_b128 v[86:89], v186 offset:2048
	ds_read_b128 v[74:77], v185 offset:4096
	ds_read_b128 v[78:81], v186 offset:4096
	ds_read_b128 v[66:69], v185 offset:6144
	ds_read_b128 v[70:73], v186 offset:6144
	s_waitcnt lgkmcnt(8)
	v_mfma_scale_f32_32x32x64_f8f6f4 v[98:113], v[222:229], v[130:137], v[98:113], v194, v193 op_sel_hi:[0,0,0]
	v_mov_b32_e32 v0, v219
	s_nop 1
	v_permlane32_swap_b32_e32 v219, v0
	v_add_f32_e32 v219, v219, v0
	v_fma_f32 v209, v209, v218, v219
	v_add_u32_e32 v176, 0x2000, v176
	v_add_u32_e32 v178, 0x20000, v178
	s_mov_b64 s[20:21], 0x1000
	v_lshl_add_u64 v[180:181], v[180:181], 0, s[20:21]
	v_max_f32_e32 v177, v114, v115
	v_max3_f32 v177, v177, v116, v117
	v_max3_f32 v177, v177, v118, v119
	v_max3_f32 v177, v177, v120, v121
	v_max3_f32 v177, v177, v122, v123
	v_max3_f32 v177, v177, v124, v125
	v_max3_f32 v177, v177, v126, v127
	v_max3_f32 v177, v177, v128, v129
	s_waitcnt lgkmcnt(6)
	v_mfma_scale_f32_32x32x64_f8f6f4 v[50:65], v[246:253], v[90:97], v[50:65], v194, v194 op_sel_hi:[0,0,0]
	v_max_f32_e32 v0, v98, v99
	v_max3_f32 v0, v0, v100, v101
	v_max3_f32 v0, v0, v102, v103
	s_waitcnt lgkmcnt(4)
	v_mfma_scale_f32_32x32x64_f8f6f4 v[34:49], v[246:253], v[82:89], v[34:49], v194, v194 op_sel_hi:[0,0,0]
	v_max3_f32 v0, v0, v104, v105
	v_max3_f32 v0, v0, v106, v107
	v_max3_f32 v0, v0, v108, v109
	s_waitcnt lgkmcnt(2)
	v_mfma_scale_f32_32x32x64_f8f6f4 v[18:33], v[246:253], v[74:81], v[18:33], v194, v194 op_sel_hi:[0,0,0]
	v_max3_f32 v0, v0, v110, v111
	v_max3_f32 v0, v0, v112, v113
	v_max_f32_e32 v177, v177, v0
	v_mov_b32_e32 v0, v177
	v_mov_b32_e32 v221, 1.0
	s_waitcnt vmcnt(0)
	ds_write_b128 v210, v[158:161] offset:43008
	ds_write_b128 v211, v[162:165] offset:51200
	ds_write_b128 v212, v[154:157] offset:59392
	s_waitcnt lgkmcnt(3)
	v_mfma_scale_f32_32x32x64_f8f6f4 v[2:17], v[246:253], v[66:73], v[2:17], v194, v194 op_sel_hi:[0,0,0]
	s_waitcnt lgkmcnt(0)
	s_barrier
	v_permlane32_swap_b32_e32 v177, v0
	v_max_f32_e32 v177, v177, v0
	v_cmp_ge_f32_e32 vcc, s90, v177
	s_cmp_eq_u64 vcc, exec
	s_cbranch_scc0 .Lmla_h0_newmax
; __device__ __forceinline__ void finishSM9(f32x16& p0, f32x16& p1, float alpha, float& l_reg, v8i32& p8) {
; #pragma unroll
;   for (int r = 0; r < 16; ++r) { p0[r] = __builtin_amdgcn_exp2f(p0[r]); p1[r] = __builtin_amdgcn_exp2f(p1[r]); }
;   float ps = 0;
; #pragma unroll
;   for (int r = 0; r < 16; ++r) ps += p0[r];
; #pragma unroll
;   for (int r = 0; r < 16; ++r) ps += p1[r];
;   { auto rr = __builtin_amdgcn_permlane32_swap(__float_as_uint(ps), __float_as_uint(ps), false, false);
;     ps = __uint_as_float(rr[0]) + __uint_as_float(rr[1]); }
;   l_reg = l_reg * alpha + ps;
; #pragma unroll
;   for (int g = 0; g < 4; ++g) {
;     int w = __builtin_amdgcn_cvt_pk_fp8_f32(p0[4 * g], p0[4 * g + 1], 0, false); p8[g] = __builtin_amdgcn_cvt_pk_fp8_f32(p0[4 * g + 2], p0[4 * g + 3], w, true);
;     int u = __builtin_amdgcn_cvt_pk_fp8_f32(p1[4 * g], p1[4 * g + 1], 0, false); p8[4 + g] = __builtin_amdgcn_cvt_pk_fp8_f32(p1[4 * g + 2], p1[4 * g + 3], u, true); }
; }
; __device__ __forceinline__ void pv8(f32x16* o, const char* Vt, const v8i32 p8, int r32, int hi) {
;   const int sw = (r32 >> 2) & 3, a0 = r32 * 64 + (((hi * 2) ^ sw) << 4), a1 = r32 * 64 + (((hi * 2 + 1) ^ sw) << 4);
; #pragma unroll
;   for (int d0 = 0; d0 < 4; ++d0) {
;     const v8i32 vf = cat8(*reinterpret_cast<const v4i32*>(Vt + d0 * 2048 + a0), *reinterpret_cast<const v4i32*>(Vt + d0 * 2048 + a1));
;     o[d0] = __builtin_amdgcn_mfma_scale_f32_32x32x64_f8f6f4(p8, vf, o[d0], 0, 0, 0, 127, 0, 127); }
; }
; __device__ __forceinline__ void qkt9(f32x16& p0, f32x16& p1, const char* Kn, const char* Kr, const v8i32* qf, const float init, int r32, int hi) {
; #pragma unroll
;   for (int r = 0; r < 16; ++r) { p0[r] = init; p1[r] = init; }
; #pragma unroll
;   for (int s = 0; s < 2; ++s) { const int c0 = s * 4 + hi * 2;
;     const v8i32 a0 = cat8(*reinterpret_cast<const v4i32*>(Kn + KN8SW(r32, c0)), *reinterpret_cast<const v4i32*>(Kn + KN8SW(r32, c0 + 1)));
;     const v8i32 a1 = cat8(*reinterpret_cast<const v4i32*>(Kn + 4096 + KN8SW(r32, c0)), *reinterpret_cast<const v4i32*>(Kn + 4096 + KN8SW(r32, c0 + 1)));
;     p0 = __builtin_amdgcn_mfma_scale_f32_32x32x64_f8f6f4(a0, qf[s], p0, 0, 0, 0, 127, 0, 124);
;     p1 = __builtin_amdgcn_mfma_scale_f32_32x32x64_f8f6f4(a1, qf[s], p1, 0, 0, 0, 127, 0, 124); }
;   { const int c0 = hi * 2;
.Lmla_h0_cont:
	ds_read_b128 v[82:85], v215 offset:51200
	ds_read_b128 v[86:89], v216 offset:51200
	ds_read_b128 v[222:225], v215 offset:55296
	ds_read_b128 v[226:229], v216 offset:55296
	global_load_dwordx4 v[158:161], v176, s[18:19]
	global_load_dwordx4 v[162:165], v178, s[16:17]
	global_load_dwordx4 v[154:157], v[180:181], off
	v_exp_f32_e32 v0, v114
	v_exp_f32_e32 v177, v115
	v_exp_f32_e32 v179, v116
	v_exp_f32_e32 v254, v117
	v_add_f32_e32 v219, v0, v177
	v_cvt_pk_fp8_f32 v246, v0, v177
	v_add_f32_e32 v219, v179, v219
	v_add_f32_e32 v219, v254, v219
	v_cvt_pk_fp8_f32 v246, v179, v254 op_sel:[0,0,1]
	s_waitcnt lgkmcnt(2)
	v_mfma_scale_f32_32x32x64_f8f6f4 v[82:97], v[82:89], v[146:153], v[230:245], v194, v193 op_sel_hi:[0,0,0]
	v_exp_f32_e32 v0, v118
	v_exp_f32_e32 v177, v119
	v_exp_f32_e32 v179, v120
	v_exp_f32_e32 v254, v121
	v_add_f32_e32 v219, v0, v219
	v_add_f32_e32 v219, v177, v219
	v_cvt_pk_fp8_f32 v247, v0, v177
	v_add_f32_e32 v219, v179, v219
	v_add_f32_e32 v219, v254, v219
	v_cvt_pk_fp8_f32 v247, v179, v254 op_sel:[0,0,1]
	ds_read_b128 v[114:117], v213 offset:51200
	ds_read_b128 v[118:121], v214 offset:51200
	s_waitcnt lgkmcnt(2)
	v_mfma_scale_f32_32x32x64_f8f6f4 v[66:81], v[222:229], v[146:153], v[230:245], v194, v193 op_sel_hi:[0,0,0]
	ds_read_b128 v[222:225], v213 offset:55296
	ds_read_b128 v[226:229], v214 offset:55296
	v_exp_f32_e32 v0, v122
	v_exp_f32_e32 v177, v123
	v_exp_f32_e32 v179, v124
	v_exp_f32_e32 v254, v125
	v_add_f32_e32 v219, v0, v219
	v_add_f32_e32 v219, v177, v219
	v_cvt_pk_fp8_f32 v248, v0, v177
	v_add_f32_e32 v219, v179, v219
	v_add_f32_e32 v219, v254, v219
	v_cvt_pk_fp8_f32 v248, v179, v254 op_sel:[0,0,1]
	v_exp_f32_e32 v0, v126
	v_exp_f32_e32 v177, v127
	v_exp_f32_e32 v179, v128
	v_exp_f32_e32 v254, v129
	v_add_f32_e32 v219, v0, v219
	v_add_f32_e32 v219, v177, v219
	v_cvt_pk_fp8_f32 v249, v0, v177
	v_add_f32_e32 v219, v179, v219
	v_add_f32_e32 v219, v254, v219
	v_cvt_pk_fp8_f32 v249, v179, v254 op_sel:[0,0,1]
	ds_read_b128 v[122:125], v185 offset:59392
	ds_read_b128 v[126:129], v186 offset:59392
	s_waitcnt lgkmcnt(4)
	v_mfma_scale_f32_32x32x64_f8f6f4 v[82:97], v[114:121], v[138:145], v[82:97], v194, v193 op_sel_hi:[0,0,0]
	v_exp_f32_e32 v0, v98
	v_exp_f32_e32 v177, v99
	v_exp_f32_e32 v179, v100
	v_exp_f32_e32 v254, v101
	v_add_f32_e32 v219, v0, v219
	v_add_f32_e32 v219, v177, v219
	v_cvt_pk_fp8_f32 v250, v0, v177
	v_add_f32_e32 v219, v179, v219
	v_add_f32_e32 v219, v254, v219
	v_cvt_pk_fp8_f32 v250, v179, v254 op_sel:[0,0,1]
	s_waitcnt lgkmcnt(2)
	v_mfma_scale_f32_32x32x64_f8f6f4 v[66:81], v[222:229], v[138:145], v[66:81], v194, v193 op_sel_hi:[0,0,0]
	ds_read_b128 v[222:225], v185 offset:61440
	ds_read_b128 v[226:229], v186 offset:61440
	v_exp_f32_e32 v0, v102
	v_exp_f32_e32 v177, v103
	v_exp_f32_e32 v179, v104
	v_exp_f32_e32 v254, v105
	v_add_f32_e32 v219, v0, v219
	v_add_f32_e32 v219, v177, v219
	v_cvt_pk_fp8_f32 v251, v0, v177
	v_add_f32_e32 v219, v179, v219
	v_add_f32_e32 v219, v254, v219
	v_cvt_pk_fp8_f32 v251, v179, v254 op_sel:[0,0,1]
	v_exp_f32_e32 v0, v106
	v_exp_f32_e32 v177, v107
	v_exp_f32_e32 v179, v108
	v_exp_f32_e32 v254, v109
	v_add_f32_e32 v219, v0, v219
	v_add_f32_e32 v219, v177, v219
	v_cvt_pk_fp8_f32 v252, v0, v177
	v_add_f32_e32 v219, v179, v219
	v_add_f32_e32 v219, v254, v219
	v_cvt_pk_fp8_f32 v252, v179, v254 op_sel:[0,0,1]
	s_waitcnt lgkmcnt(2)
	v_mfma_scale_f32_32x32x64_f8f6f4 v[82:97], v[122:129], v[130:137], v[82:97], v194, v193 op_sel_hi:[0,0,0]
	v_exp_f32_e32 v0, v110
	v_exp_f32_e32 v177, v111
	v_exp_f32_e32 v179, v112
	v_exp_f32_e32 v254, v113
	v_add_f32_e32 v219, v0, v219
	v_add_f32_e32 v219, v177, v219
	v_cvt_pk_fp8_f32 v253, v0, v177
	v_add_f32_e32 v219, v179, v219
	v_add_f32_e32 v219, v254, v219
	v_cvt_pk_fp8_f32 v253, v179, v254 op_sel:[0,0,1]
	ds_read_b128 v[122:125], v185 offset:8192
	ds_read_b128 v[126:129], v186 offset:8192
	ds_read_b128 v[114:117], v185 offset:10240
	ds_read_b128 v[118:121], v186 offset:10240
	ds_read_b128 v[106:109], v185 offset:12288
	ds_read_b128 v[110:113], v186 offset:12288
	ds_read_b128 v[98:101], v185 offset:14336
	ds_read_b128 v[102:105], v186 offset:14336
	s_waitcnt lgkmcnt(8)
	v_mfma_scale_f32_32x32x64_f8f6f4 v[66:81], v[222:229], v[130:137], v[66:81], v194, v193 op_sel_hi:[0,0,0]
	v_mov_b32_e32 v0, v219
	s_nop 1
	v_permlane32_swap_b32_e32 v219, v0
	v_add_f32_e32 v219, v219, v0
	v_fma_f32 v209, v209, v221, v219
	v_add_u32_e32 v176, 0x2000, v176
	v_add_u32_e32 v178, 0x20000, v178
	s_mov_b64 s[20:21], 0x1000
	v_lshl_add_u64 v[180:181], v[180:181], 0, s[20:21]
	v_max_f32_e32 v177, v82, v83
	v_max3_f32 v177, v177, v84, v85
	v_max3_f32 v177, v177, v86, v87
	v_max3_f32 v177, v177, v88, v89
	v_max3_f32 v177, v177, v90, v91
	v_max3_f32 v177, v177, v92, v93
	v_max3_f32 v177, v177, v94, v95
	v_max3_f32 v177, v177, v96, v97
	s_waitcnt lgkmcnt(6)
	v_mfma_scale_f32_32x32x64_f8f6f4 v[50:65], v[246:253], v[122:129], v[50:65], v194, v194 op_sel_hi:[0,0,0]
	v_max_f32_e32 v0, v66, v67
	v_max3_f32 v0, v0, v68, v69
	v_max3_f32 v0, v0, v70, v71
	s_waitcnt lgkmcnt(4)
	v_mfma_scale_f32_32x32x64_f8f6f4 v[34:49], v[246:253], v[114:121], v[34:49], v194, v194 op_sel_hi:[0,0,0]
	v_max3_f32 v0, v0, v72, v73
	v_max3_f32 v0, v0, v74, v75
	v_max3_f32 v0, v0, v76, v77
	s_waitcnt lgkmcnt(2)
	v_mfma_scale_f32_32x32x64_f8f6f4 v[18:33], v[246:253], v[106:113], v[18:33], v194, v194 op_sel_hi:[0,0,0]
	v_max3_f32 v0, v0, v78, v79
	v_max3_f32 v0, v0, v80, v81
	v_max_f32_e32 v177, v177, v0
	v_mov_b32_e32 v0, v177
	v_mov_b32_e32 v218, 1.0
	s_waitcnt vmcnt(0)
	ds_write_b128 v210, v[158:161]
	ds_write_b128 v211, v[162:165] offset:16384
	ds_write_b128 v212, v[154:157] offset:32768
	s_waitcnt lgkmcnt(3)
	v_mfma_scale_f32_32x32x64_f8f6f4 v[2:17], v[246:253], v[98:105], v[2:17], v194, v194 op_sel_hi:[0,0,0]
	s_waitcnt lgkmcnt(0)
	s_barrier
	v_permlane32_swap_b32_e32 v177, v0
	v_max_f32_e32 v177, v177, v0
	v_cmp_ge_f32_e32 vcc, s90, v177
	s_cmp_eq_u64 vcc, exec
	s_cbranch_scc0 .Lmla_h1_newmax
; __device__ __forceinline__ void finishSM9(f32x16& p0, f32x16& p1, float alpha, float& l_reg, v8i32& p8) {
; #pragma unroll
;   for (int r = 0; r < 16; ++r) { p0[r] = __builtin_amdgcn_exp2f(p0[r]); p1[r] = __builtin_amdgcn_exp2f(p1[r]); }
;   float ps = 0;
; #pragma unroll
;   for (int r = 0; r < 16; ++r) ps += p0[r];
; #pragma unroll
;   for (int r = 0; r < 16; ++r) ps += p1[r];
;   { auto rr = __builtin_amdgcn_permlane32_swap(__float_as_uint(ps), __float_as_uint(ps), false, false);
;     ps = __uint_as_float(rr[0]) + __uint_as_float(rr[1]); }
;   l_reg = l_reg * alpha + ps;
; #pragma unroll
;   for (int g = 0; g < 4; ++g) {
;     int w = __builtin_amdgcn_cvt_pk_fp8_f32(p0[4 * g], p0[4 * g + 1], 0, false); p8[g] = __builtin_amdgcn_cvt_pk_fp8_f32(p0[4 * g + 2], p0[4 * g + 3], w, true);
;     int u = __builtin_amdgcn_cvt_pk_fp8_f32(p1[4 * g], p1[4 * g + 1], 0, false); p8[4 + g] = __builtin_amdgcn_cvt_pk_fp8_f32(p1[4 * g + 2], p1[4 * g + 3], u, true); }
; }
; __device__ __forceinline__ void pv8(f32x16* o, const char* Vt, const v8i32 p8, int r32, int hi) {
;   const int sw = (r32 >> 2) & 3, a0 = r32 * 64 + (((hi * 2) ^ sw) << 4), a1 = r32 * 64 + (((hi * 2 + 1) ^ sw) << 4);
; #pragma unroll
;   for (int d0 = 0; d0 < 4; ++d0) {
;     const v8i32 vf = cat8(*reinterpret_cast<const v4i32*>(Vt + d0 * 2048 + a0), *reinterpret_cast<const v4i32*>(Vt + d0 * 2048 + a1));
;     o[d0] = __builtin_amdgcn_mfma_scale_f32_32x32x64_f8f6f4(p8, vf, o[d0], 0, 0, 0, 127, 0, 127); }
; }
; __device__ __forceinline__ void qkt9(f32x16& p0, f32x16& p1, const char* Kn, const char* Kr, const v8i32* qf, const float init, int r32, int hi) {
; #pragma unroll
;   for (int r = 0; r < 16; ++r) { p0[r] = init; p1[r] = init; }
; #pragma unroll
;   for (int s = 0; s < 2; ++s) { const int c0 = s * 4 + hi * 2;
;     const v8i32 a0 = cat8(*reinterpret_cast<const v4i32*>(Kn + KN8SW(r32, c0)), *reinterpret_cast<const v4i32*>(Kn + KN8SW(r32, c0 + 1)));
;     const v8i32 a1 = cat8(*reinterpret_cast<const v4i32*>(Kn + 4096 + KN8SW(r32, c0)), *reinterpret_cast<const v4i32*>(Kn + 4096 + KN8SW(r32, c0 + 1)));
;     p0 = __builtin_amdgcn_mfma_scale_f32_32x32x64_f8f6f4(a0, qf[s], p0, 0, 0, 0, 127, 0, 124);
;     p1 = __builtin_amdgcn_mfma_scale_f32_32x32x64_f8f6f4(a1, qf[s], p1, 0, 0, 0, 127, 0, 124); }
;   { const int c0 = hi * 2;
.Lmla_h1_cont:
	ds_read_b128 v[114:117], v215 offset:16384
	ds_read_b128 v[118:121], v216 offset:16384
	ds_read_b128 v[222:225], v215 offset:20480
	ds_read_b128 v[226:229], v216 offset:20480
	global_load_dwordx4 v[158:161], v176, s[18:19]
	global_load_dwordx4 v[162:165], v178, s[16:17]
	global_load_dwordx4 v[154:157], v[180:181], off
	v_exp_f32_e32 v0, v82
	v_exp_f32_e32 v177, v83
	v_exp_f32_e32 v179, v84
	v_exp_f32_e32 v254, v85
	v_add_f32_e32 v219, v0, v177
	v_cvt_pk_fp8_f32 v246, v0, v177
	v_add_f32_e32 v219, v179, v219
	v_add_f32_e32 v219, v254, v219
	v_cvt_pk_fp8_f32 v246, v179, v254 op_sel:[0,0,1]
	s_waitcnt lgkmcnt(2)
	v_mfma_scale_f32_32x32x64_f8f6f4 v[114:129], v[114:121], v[146:153], v[230:245], v194, v193 op_sel_hi:[0,0,0]
	v_exp_f32_e32 v0, v86
	v_exp_f32_e32 v177, v87
	v_exp_f32_e32 v179, v88
	v_exp_f32_e32 v254, v89
	v_add_f32_e32 v219, v0, v219
	v_add_f32_e32 v219, v177, v219
	v_cvt_pk_fp8_f32 v247, v0, v177
	v_add_f32_e32 v219, v179, v219
	v_add_f32_e32 v219, v254, v219
	v_cvt_pk_fp8_f32 v247, v179, v254 op_sel:[0,0,1]
	ds_read_b128 v[82:85], v213 offset:16384
	ds_read_b128 v[86:89], v214 offset:16384
	s_waitcnt lgkmcnt(2)
	v_mfma_scale_f32_32x32x64_f8f6f4 v[98:113], v[222:229], v[146:153], v[230:245], v194, v193 op_sel_hi:[0,0,0]
	ds_read_b128 v[222:225], v213 offset:20480
	ds_read_b128 v[226:229], v214 offset:20480
	v_exp_f32_e32 v0, v90
	v_exp_f32_e32 v177, v91
	v_exp_f32_e32 v179, v92
	v_exp_f32_e32 v254, v93
	v_add_f32_e32 v219, v0, v219
	v_add_f32_e32 v219, v177, v219
	v_cvt_pk_fp8_f32 v248, v0, v177
	v_add_f32_e32 v219, v179, v219
	v_add_f32_e32 v219, v254, v219
	v_cvt_pk_fp8_f32 v248, v179, v254 op_sel:[0,0,1]
	v_exp_f32_e32 v0, v94
	v_exp_f32_e32 v177, v95
	v_exp_f32_e32 v179, v96
	v_exp_f32_e32 v254, v97
	v_add_f32_e32 v219, v0, v219
	v_add_f32_e32 v219, v177, v219
	v_cvt_pk_fp8_f32 v249, v0, v177
	v_add_f32_e32 v219, v179, v219
	v_add_f32_e32 v219, v254, v219
	v_cvt_pk_fp8_f32 v249, v179, v254 op_sel:[0,0,1]
	ds_read_b128 v[90:93], v185 offset:32768
	ds_read_b128 v[94:97], v186 offset:32768
	s_waitcnt lgkmcnt(4)
	v_mfma_scale_f32_32x32x64_f8f6f4 v[114:129], v[82:89], v[138:145], v[114:129], v194, v193 op_sel_hi:[0,0,0]
	v_exp_f32_e32 v0, v66
	v_exp_f32_e32 v177, v67
	v_exp_f32_e32 v179, v68
	v_exp_f32_e32 v254, v69
	v_add_f32_e32 v219, v0, v219
	v_add_f32_e32 v219, v177, v219
	v_cvt_pk_fp8_f32 v250, v0, v177
	v_add_f32_e32 v219, v179, v219
	v_add_f32_e32 v219, v254, v219
	v_cvt_pk_fp8_f32 v250, v179, v254 op_sel:[0,0,1]
	s_waitcnt lgkmcnt(2)
	v_mfma_scale_f32_32x32x64_f8f6f4 v[98:113], v[222:229], v[138:145], v[98:113], v194, v193 op_sel_hi:[0,0,0]
	ds_read_b128 v[222:225], v185 offset:34816
	ds_read_b128 v[226:229], v186 offset:34816
	v_exp_f32_e32 v0, v70
	v_exp_f32_e32 v177, v71
	v_exp_f32_e32 v179, v72
	v_exp_f32_e32 v254, v73
	v_add_f32_e32 v219, v0, v219
	v_add_f32_e32 v219, v177, v219
	v_cvt_pk_fp8_f32 v251, v0, v177
	v_add_f32_e32 v219, v179, v219
	v_add_f32_e32 v219, v254, v219
	v_cvt_pk_fp8_f32 v251, v179, v254 op_sel:[0,0,1]
	v_exp_f32_e32 v0, v74
	v_exp_f32_e32 v177, v75
	v_exp_f32_e32 v179, v76
	v_exp_f32_e32 v254, v77
	v_add_f32_e32 v219, v0, v219
	v_add_f32_e32 v219, v177, v219
	v_cvt_pk_fp8_f32 v252, v0, v177
	v_add_f32_e32 v219, v179, v219
	v_add_f32_e32 v219, v254, v219
	v_cvt_pk_fp8_f32 v252, v179, v254 op_sel:[0,0,1]
	s_waitcnt lgkmcnt(2)
	v_mfma_scale_f32_32x32x64_f8f6f4 v[114:129], v[90:97], v[130:137], v[114:129], v194, v193 op_sel_hi:[0,0,0]
	v_exp_f32_e32 v0, v78
	v_exp_f32_e32 v177, v79
	v_exp_f32_e32 v179, v80
	v_exp_f32_e32 v254, v81
	v_add_f32_e32 v219, v0, v219
	v_add_f32_e32 v219, v177, v219
	v_cvt_pk_fp8_f32 v253, v0, v177
	v_add_f32_e32 v219, v179, v219
	v_add_f32_e32 v219, v254, v219
	v_cvt_pk_fp8_f32 v253, v179, v254 op_sel:[0,0,1]
	ds_read_b128 v[90:93], v185 offset:43008
	ds_read_b128 v[94:97], v186 offset:43008
	ds_read_b128 v[82:85], v185 offset:45056
	ds_read_b128 v[86:89], v186 offset:45056
	ds_read_b128 v[74:77], v185 offset:47104
	ds_read_b128 v[78:81], v186 offset:47104
	ds_read_b128 v[66:69], v185 offset:49152
	ds_read_b128 v[70:73], v186 offset:49152
	s_waitcnt lgkmcnt(8)
	v_mfma_scale_f32_32x32x64_f8f6f4 v[98:113], v[222:229], v[130:137], v[98:113], v194, v193 op_sel_hi:[0,0,0]
	v_mov_b32_e32 v0, v219
	s_nop 1
	v_permlane32_swap_b32_e32 v219, v0
	v_add_f32_e32 v219, v219, v0
	v_fma_f32 v209, v209, v218, v219
	v_add_u32_e32 v176, 0x2000, v176
	v_add_u32_e32 v178, 0x20000, v178
	s_mov_b64 s[20:21], 0x1000
	v_lshl_add_u64 v[180:181], v[180:181], 0, s[20:21]
	v_max_f32_e32 v177, v114, v115
	v_max3_f32 v177, v177, v116, v117
	v_max3_f32 v177, v177, v118, v119
	v_max3_f32 v177, v177, v120, v121
	v_max3_f32 v177, v177, v122, v123
	v_max3_f32 v177, v177, v124, v125
	v_max3_f32 v177, v177, v126, v127
	v_max3_f32 v177, v177, v128, v129
	s_waitcnt lgkmcnt(6)
	v_mfma_scale_f32_32x32x64_f8f6f4 v[50:65], v[246:253], v[90:97], v[50:65], v194, v194 op_sel_hi:[0,0,0]
	v_max_f32_e32 v0, v98, v99
	v_max3_f32 v0, v0, v100, v101
	v_max3_f32 v0, v0, v102, v103
	s_waitcnt lgkmcnt(4)
	v_mfma_scale_f32_32x32x64_f8f6f4 v[34:49], v[246:253], v[82:89], v[34:49], v194, v194 op_sel_hi:[0,0,0]
	v_max3_f32 v0, v0, v104, v105
	v_max3_f32 v0, v0, v106, v107
	v_max3_f32 v0, v0, v108, v109
	s_waitcnt lgkmcnt(2)
	v_mfma_scale_f32_32x32x64_f8f6f4 v[18:33], v[246:253], v[74:81], v[18:33], v194, v194 op_sel_hi:[0,0,0]
	v_max3_f32 v0, v0, v110, v111
	v_max3_f32 v0, v0, v112, v113
	v_max_f32_e32 v177, v177, v0
	v_mov_b32_e32 v0, v177
	v_mov_b32_e32 v221, 1.0
	s_waitcnt vmcnt(0)
	ds_write_b128 v210, v[158:161] offset:8192
	ds_write_b128 v211, v[162:165] offset:24576
	ds_write_b128 v212, v[154:157] offset:36864
	s_waitcnt lgkmcnt(3)
	v_mfma_scale_f32_32x32x64_f8f6f4 v[2:17], v[246:253], v[66:73], v[2:17], v194, v194 op_sel_hi:[0,0,0]
	s_waitcnt lgkmcnt(0)
	s_barrier
	v_permlane32_swap_b32_e32 v177, v0
	v_max_f32_e32 v177, v177, v0
	v_cmp_ge_f32_e32 vcc, s90, v177
	s_cmp_eq_u64 vcc, exec
	s_cbranch_scc0 .Lmla_h2_newmax
; __device__ __forceinline__ void finishSM9(f32x16& p0, f32x16& p1, float alpha, float& l_reg, v8i32& p8) {
; #pragma unroll
;   for (int r = 0; r < 16; ++r) { p0[r] = __builtin_amdgcn_exp2f(p0[r]); p1[r] = __builtin_amdgcn_exp2f(p1[r]); }
;   float ps = 0;
; #pragma unroll
;   for (int r = 0; r < 16; ++r) ps += p0[r];
; #pragma unroll
;   for (int r = 0; r < 16; ++r) ps += p1[r];
;   { auto rr = __builtin_amdgcn_permlane32_swap(__float_as_uint(ps), __float_as_uint(ps), false, false);
;     ps = __uint_as_float(rr[0]) + __uint_as_float(rr[1]); }
;   l_reg = l_reg * alpha + ps;
; #pragma unroll
;   for (int g = 0; g < 4; ++g) {
;     int w = __builtin_amdgcn_cvt_pk_fp8_f32(p0[4 * g], p0[4 * g + 1], 0, false); p8[g] = __builtin_amdgcn_cvt_pk_fp8_f32(p0[4 * g + 2], p0[4 * g + 3], w, true);
;     int u = __builtin_amdgcn_cvt_pk_fp8_f32(p1[4 * g], p1[4 * g + 1], 0, false); p8[4 + g] = __builtin_amdgcn_cvt_pk_fp8_f32(p1[4 * g + 2], p1[4 * g + 3], u, true); }
; }
; __device__ __forceinline__ void pv8(f32x16* o, const char* Vt, const v8i32 p8, int r32, int hi) {
;   const int sw = (r32 >> 2) & 3, a0 = r32 * 64 + (((hi * 2) ^ sw) << 4), a1 = r32 * 64 + (((hi * 2 + 1) ^ sw) << 4);
; #pragma unroll
;   for (int d0 = 0; d0 < 4; ++d0) {
;     const v8i32 vf = cat8(*reinterpret_cast<const v4i32*>(Vt + d0 * 2048 + a0), *reinterpret_cast<const v4i32*>(Vt + d0 * 2048 + a1));
;     o[d0] = __builtin_amdgcn_mfma_scale_f32_32x32x64_f8f6f4(p8, vf, o[d0], 0, 0, 0, 127, 0, 127); }
; }
; __device__ __forceinline__ void qkt9(f32x16& p0, f32x16& p1, const char* Kn, const char* Kr, const v8i32* qf, const float init, int r32, int hi) {
; #pragma unroll
;   for (int r = 0; r < 16; ++r) { p0[r] = init; p1[r] = init; }
; #pragma unroll
;   for (int s = 0; s < 2; ++s) { const int c0 = s * 4 + hi * 2;
;     const v8i32 a0 = cat8(*reinterpret_cast<const v4i32*>(Kn + KN8SW(r32, c0)), *reinterpret_cast<const v4i32*>(Kn + KN8SW(r32, c0 + 1)));
;     const v8i32 a1 = cat8(*reinterpret_cast<const v4i32*>(Kn + 4096 + KN8SW(r32, c0)), *reinterpret_cast<const v4i32*>(Kn + 4096 + KN8SW(r32, c0 + 1)));
;     p0 = __builtin_amdgcn_mfma_scale_f32_32x32x64_f8f6f4(a0, qf[s], p0, 0, 0, 0, 127, 0, 124);
;     p1 = __builtin_amdgcn_mfma_scale_f32_32x32x64_f8f6f4(a1, qf[s], p1, 0, 0, 0, 127, 0, 124); }
;   { const int c0 = hi * 2;
.Lmla_h2_cont:
	ds_read_b128 v[82:85], v215 offset:24576
	ds_read_b128 v[86:89], v216 offset:24576
	ds_read_b128 v[222:225], v215 offset:28672
	ds_read_b128 v[226:229], v216 offset:28672
	global_load_dwordx4 v[158:161], v176, s[18:19]
	global_load_dwordx4 v[162:165], v178, s[16:17]
	global_load_dwordx4 v[154:157], v[180:181], off
	v_exp_f32_e32 v0, v114
	v_exp_f32_e32 v177, v115
	v_exp_f32_e32 v179, v116
	v_exp_f32_e32 v254, v117
	v_add_f32_e32 v219, v0, v177
	v_cvt_pk_fp8_f32 v246, v0, v177
	v_add_f32_e32 v219, v179, v219
	v_add_f32_e32 v219, v254, v219
	v_cvt_pk_fp8_f32 v246, v179, v254 op_sel:[0,0,1]
	s_waitcnt lgkmcnt(2)
	v_mfma_scale_f32_32x32x64_f8f6f4 v[82:97], v[82:89], v[146:153], v[230:245], v194, v193 op_sel_hi:[0,0,0]
	v_exp_f32_e32 v0, v118
	v_exp_f32_e32 v177, v119
	v_exp_f32_e32 v179, v120
	v_exp_f32_e32 v254, v121
	v_add_f32_e32 v219, v0, v219
	v_add_f32_e32 v219, v177, v219
	v_cvt_pk_fp8_f32 v247, v0, v177
	v_add_f32_e32 v219, v179, v219
	v_add_f32_e32 v219, v254, v219
	v_cvt_pk_fp8_f32 v247, v179, v254 op_sel:[0,0,1]
	ds_read_b128 v[114:117], v213 offset:24576
	ds_read_b128 v[118:121], v214 offset:24576
	s_waitcnt lgkmcnt(2)
	v_mfma_scale_f32_32x32x64_f8f6f4 v[66:81], v[222:229], v[146:153], v[230:245], v194, v193 op_sel_hi:[0,0,0]
	ds_read_b128 v[222:225], v213 offset:28672
	ds_read_b128 v[226:229], v214 offset:28672
	v_exp_f32_e32 v0, v122
	v_exp_f32_e32 v177, v123
	v_exp_f32_e32 v179, v124
	v_exp_f32_e32 v254, v125
	v_add_f32_e32 v219, v0, v219
	v_add_f32_e32 v219, v177, v219
	v_cvt_pk_fp8_f32 v248, v0, v177
	v_add_f32_e32 v219, v179, v219
	v_add_f32_e32 v219, v254, v219
	v_cvt_pk_fp8_f32 v248, v179, v254 op_sel:[0,0,1]
	v_exp_f32_e32 v0, v126
	v_exp_f32_e32 v177, v127
	v_exp_f32_e32 v179, v128
	v_exp_f32_e32 v254, v129
	v_add_f32_e32 v219, v0, v219
	v_add_f32_e32 v219, v177, v219
	v_cvt_pk_fp8_f32 v249, v0, v177
	v_add_f32_e32 v219, v179, v219
	v_add_f32_e32 v219, v254, v219
	v_cvt_pk_fp8_f32 v249, v179, v254 op_sel:[0,0,1]
	ds_read_b128 v[122:125], v185 offset:36864
	ds_read_b128 v[126:129], v186 offset:36864
	s_waitcnt lgkmcnt(4)
	v_mfma_scale_f32_32x32x64_f8f6f4 v[82:97], v[114:121], v[138:145], v[82:97], v194, v193 op_sel_hi:[0,0,0]
	v_exp_f32_e32 v0, v98
	v_exp_f32_e32 v177, v99
	v_exp_f32_e32 v179, v100
	v_exp_f32_e32 v254, v101
	v_add_f32_e32 v219, v0, v219
	v_add_f32_e32 v219, v177, v219
	v_cvt_pk_fp8_f32 v250, v0, v177
	v_add_f32_e32 v219, v179, v219
	v_add_f32_e32 v219, v254, v219
	v_cvt_pk_fp8_f32 v250, v179, v254 op_sel:[0,0,1]
	s_waitcnt lgkmcnt(2)
	v_mfma_scale_f32_32x32x64_f8f6f4 v[66:81], v[222:229], v[138:145], v[66:81], v194, v193 op_sel_hi:[0,0,0]
	ds_read_b128 v[222:225], v185 offset:38912
	ds_read_b128 v[226:229], v186 offset:38912
	v_exp_f32_e32 v0, v102
	v_exp_f32_e32 v177, v103
	v_exp_f32_e32 v179, v104
	v_exp_f32_e32 v254, v105
	v_add_f32_e32 v219, v0, v219
	v_add_f32_e32 v219, v177, v219
	v_cvt_pk_fp8_f32 v251, v0, v177
	v_add_f32_e32 v219, v179, v219
	v_add_f32_e32 v219, v254, v219
	v_cvt_pk_fp8_f32 v251, v179, v254 op_sel:[0,0,1]
	v_exp_f32_e32 v0, v106
	v_exp_f32_e32 v177, v107
	v_exp_f32_e32 v179, v108
	v_exp_f32_e32 v254, v109
	v_add_f32_e32 v219, v0, v219
	v_add_f32_e32 v219, v177, v219
	v_cvt_pk_fp8_f32 v252, v0, v177
	v_add_f32_e32 v219, v179, v219
	v_add_f32_e32 v219, v254, v219
	v_cvt_pk_fp8_f32 v252, v179, v254 op_sel:[0,0,1]
	s_waitcnt lgkmcnt(2)
	v_mfma_scale_f32_32x32x64_f8f6f4 v[82:97], v[122:129], v[130:137], v[82:97], v194, v193 op_sel_hi:[0,0,0]
	v_exp_f32_e32 v0, v110
	v_exp_f32_e32 v177, v111
	v_exp_f32_e32 v179, v112
	v_exp_f32_e32 v254, v113
	v_add_f32_e32 v219, v0, v219
	v_add_f32_e32 v219, v177, v219
	v_cvt_pk_fp8_f32 v253, v0, v177
	v_add_f32_e32 v219, v179, v219
	v_add_f32_e32 v219, v254, v219
	v_cvt_pk_fp8_f32 v253, v179, v254 op_sel:[0,0,1]
	ds_read_b128 v[122:125], v185 offset:0
	ds_read_b128 v[126:129], v186 offset:0
	ds_read_b128 v[114:117], v185 offset:2048
	ds_read_b128 v[118:121], v186 offset:2048
	ds_read_b128 v[106:109], v185 offset:4096
	ds_read_b128 v[110:113], v186 offset:4096
	ds_read_b128 v[98:101], v185 offset:6144
	ds_read_b128 v[102:105], v186 offset:6144
	s_waitcnt lgkmcnt(8)
	v_mfma_scale_f32_32x32x64_f8f6f4 v[66:81], v[222:229], v[130:137], v[66:81], v194, v193 op_sel_hi:[0,0,0]
	v_mov_b32_e32 v0, v219
	s_nop 1
	v_permlane32_swap_b32_e32 v219, v0
	v_add_f32_e32 v219, v219, v0
	v_fma_f32 v209, v209, v221, v219
	v_add_u32_e32 v176, 0x2000, v176
	v_add_u32_e32 v178, 0x20000, v178
	s_mov_b64 s[20:21], 0x1000
	v_lshl_add_u64 v[180:181], v[180:181], 0, s[20:21]
	v_max_f32_e32 v177, v82, v83
	v_max3_f32 v177, v177, v84, v85
	v_max3_f32 v177, v177, v86, v87
	v_max3_f32 v177, v177, v88, v89
	v_max3_f32 v177, v177, v90, v91
	v_max3_f32 v177, v177, v92, v93
	v_max3_f32 v177, v177, v94, v95
	v_max3_f32 v177, v177, v96, v97
	s_waitcnt lgkmcnt(6)
	v_mfma_scale_f32_32x32x64_f8f6f4 v[50:65], v[246:253], v[122:129], v[50:65], v194, v194 op_sel_hi:[0,0,0]
	v_max_f32_e32 v0, v66, v67
	v_max3_f32 v0, v0, v68, v69
	v_max3_f32 v0, v0, v70, v71
	s_waitcnt lgkmcnt(4)
	v_mfma_scale_f32_32x32x64_f8f6f4 v[34:49], v[246:253], v[114:121], v[34:49], v194, v194 op_sel_hi:[0,0,0]
	v_max3_f32 v0, v0, v72, v73
	v_max3_f32 v0, v0, v74, v75
	v_max3_f32 v0, v0, v76, v77
	s_waitcnt lgkmcnt(2)
	v_mfma_scale_f32_32x32x64_f8f6f4 v[18:33], v[246:253], v[106:113], v[18:33], v194, v194 op_sel_hi:[0,0,0]
	v_max3_f32 v0, v0, v78, v79
	v_max3_f32 v0, v0, v80, v81
	v_max_f32_e32 v177, v177, v0
	v_mov_b32_e32 v0, v177
	v_mov_b32_e32 v218, 1.0
	s_waitcnt vmcnt(0)
	ds_write_b128 v210, v[158:161] offset:43008
	ds_write_b128 v211, v[162:165] offset:51200
	ds_write_b128 v212, v[154:157] offset:59392
	s_waitcnt lgkmcnt(3)
	v_mfma_scale_f32_32x32x64_f8f6f4 v[2:17], v[246:253], v[98:105], v[2:17], v194, v194 op_sel_hi:[0,0,0]
	s_waitcnt lgkmcnt(0)
	s_barrier
	v_permlane32_swap_b32_e32 v177, v0
	v_max_f32_e32 v177, v177, v0
	v_cmp_ge_f32_e32 vcc, s90, v177
	s_cmp_eq_u64 vcc, exec
	s_cbranch_scc0 .Lmla_h3_newmax
; __device__ __forceinline__ void finishSM9(f32x16& p0, f32x16& p1, float alpha, float& l_reg, v8i32& p8) {
; #pragma unroll
;   for (int r = 0; r < 16; ++r) { p0[r] = __builtin_amdgcn_exp2f(p0[r]); p1[r] = __builtin_amdgcn_exp2f(p1[r]); }
;   float ps = 0;
; #pragma unroll
;   for (int r = 0; r < 16; ++r) ps += p0[r];
; #pragma unroll
;   for (int r = 0; r < 16; ++r) ps += p1[r];
;   { auto rr = __builtin_amdgcn_permlane32_swap(__float_as_uint(ps), __float_as_uint(ps), false, false);
;     ps = __uint_as_float(rr[0]) + __uint_as_float(rr[1]); }
;   l_reg = l_reg * alpha + ps;
; #pragma unroll
;   for (int g = 0; g < 4; ++g) {
;     int w = __builtin_amdgcn_cvt_pk_fp8_f32(p0[4 * g], p0[4 * g + 1], 0, false); p8[g] = __builtin_amdgcn_cvt_pk_fp8_f32(p0[4 * g + 2], p0[4 * g + 3], w, true);
;     int u = __builtin_amdgcn_cvt_pk_fp8_f32(p1[4 * g], p1[4 * g + 1], 0, false); p8[4 + g] = __builtin_amdgcn_cvt_pk_fp8_f32(p1[4 * g + 2], p1[4 * g + 3], u, true); }
; }
; __device__ __forceinline__ void pv8(f32x16* o, const char* Vt, const v8i32 p8, int r32, int hi) {
;   const int sw = (r32 >> 2) & 3, a0 = r32 * 64 + (((hi * 2) ^ sw) << 4), a1 = r32 * 64 + (((hi * 2 + 1) ^ sw) << 4);
; #pragma unroll
;   for (int d0 = 0; d0 < 4; ++d0) {
;     const v8i32 vf = cat8(*reinterpret_cast<const v4i32*>(Vt + d0 * 2048 + a0), *reinterpret_cast<const v4i32*>(Vt + d0 * 2048 + a1));
;     o[d0] = __builtin_amdgcn_mfma_scale_f32_32x32x64_f8f6f4(p8, vf, o[d0], 0, 0, 0, 127, 0, 127); }
; }
; __device__ __forceinline__ void qkt9(f32x16& p0, f32x16& p1, const char* Kn, const char* Kr, const v8i32* qf, const float init, int r32, int hi) {
; #pragma unroll
;   for (int r = 0; r < 16; ++r) { p0[r] = init; p1[r] = init; }
; #pragma unroll
;   for (int s = 0; s < 2; ++s) { const int c0 = s * 4 + hi * 2;
;     const v8i32 a0 = cat8(*reinterpret_cast<const v4i32*>(Kn + KN8SW(r32, c0)), *reinterpret_cast<const v4i32*>(Kn + KN8SW(r32, c0 + 1)));
;     const v8i32 a1 = cat8(*reinterpret_cast<const v4i32*>(Kn + 4096 + KN8SW(r32, c0)), *reinterpret_cast<const v4i32*>(Kn + 4096 + KN8SW(r32, c0 + 1)));
;     p0 = __builtin_amdgcn_mfma_scale_f32_32x32x64_f8f6f4(a0, qf[s], p0, 0, 0, 0, 127, 0, 124);
;     p1 = __builtin_amdgcn_mfma_scale_f32_32x32x64_f8f6f4(a1, qf[s], p1, 0, 0, 0, 127, 0, 124); }
;   { const int c0 = hi * 2;
.Lmla_h3_cont:
	ds_read_b128 v[114:117], v215 offset:51200
	ds_read_b128 v[118:121], v216 offset:51200
	ds_read_b128 v[222:225], v215 offset:55296
	ds_read_b128 v[226:229], v216 offset:55296
	global_load_dwordx4 v[158:161], v176, s[18:19]
	global_load_dwordx4 v[162:165], v178, s[16:17]
	global_load_dwordx4 v[154:157], v[180:181], off
	v_exp_f32_e32 v0, v82
	v_exp_f32_e32 v177, v83
	v_exp_f32_e32 v179, v84
	v_exp_f32_e32 v254, v85
	v_add_f32_e32 v219, v0, v177
	v_cvt_pk_fp8_f32 v246, v0, v177
	v_add_f32_e32 v219, v179, v219
	v_add_f32_e32 v219, v254, v219
	v_cvt_pk_fp8_f32 v246, v179, v254 op_sel:[0,0,1]
	s_waitcnt lgkmcnt(2)
	v_mfma_scale_f32_32x32x64_f8f6f4 v[114:129], v[114:121], v[146:153], v[230:245], v194, v193 op_sel_hi:[0,0,0]
	v_exp_f32_e32 v0, v86
	v_exp_f32_e32 v177, v87
	v_exp_f32_e32 v179, v88
	v_exp_f32_e32 v254, v89
	v_add_f32_e32 v219, v0, v219
	v_add_f32_e32 v219, v177, v219
	v_cvt_pk_fp8_f32 v247, v0, v177
	v_add_f32_e32 v219, v179, v219
	v_add_f32_e32 v219, v254, v219
	v_cvt_pk_fp8_f32 v247, v179, v254 op_sel:[0,0,1]
	ds_read_b128 v[82:85], v213 offset:51200
	ds_read_b128 v[86:89], v214 offset:51200
	s_waitcnt lgkmcnt(2)
	v_mfma_scale_f32_32x32x64_f8f6f4 v[98:113], v[222:229], v[146:153], v[230:245], v194, v193 op_sel_hi:[0,0,0]
	ds_read_b128 v[222:225], v213 offset:55296
	ds_read_b128 v[226:229], v214 offset:55296
	v_exp_f32_e32 v0, v90
	v_exp_f32_e32 v177, v91
	v_exp_f32_e32 v179, v92
	v_exp_f32_e32 v254, v93
	v_add_f32_e32 v219, v0, v219
	v_add_f32_e32 v219, v177, v219
	v_cvt_pk_fp8_f32 v248, v0, v177
	v_add_f32_e32 v219, v179, v219
	v_add_f32_e32 v219, v254, v219
	v_cvt_pk_fp8_f32 v248, v179, v254 op_sel:[0,0,1]
	v_exp_f32_e32 v0, v94
	v_exp_f32_e32 v177, v95
	v_exp_f32_e32 v179, v96
	v_exp_f32_e32 v254, v97
	v_add_f32_e32 v219, v0, v219
	v_add_f32_e32 v219, v177, v219
	v_cvt_pk_fp8_f32 v249, v0, v177
	v_add_f32_e32 v219, v179, v219
	v_add_f32_e32 v219, v254, v219
	v_cvt_pk_fp8_f32 v249, v179, v254 op_sel:[0,0,1]
	ds_read_b128 v[90:93], v185 offset:59392
	ds_read_b128 v[94:97], v186 offset:59392
	s_waitcnt lgkmcnt(4)
	v_mfma_scale_f32_32x32x64_f8f6f4 v[114:129], v[82:89], v[138:145], v[114:129], v194, v193 op_sel_hi:[0,0,0]
	v_exp_f32_e32 v0, v66
	v_exp_f32_e32 v177, v67
	v_exp_f32_e32 v179, v68
	v_exp_f32_e32 v254, v69
	v_add_f32_e32 v219, v0, v219
	v_add_f32_e32 v219, v177, v219
	v_cvt_pk_fp8_f32 v250, v0, v177
	v_add_f32_e32 v219, v179, v219
	v_add_f32_e32 v219, v254, v219
	v_cvt_pk_fp8_f32 v250, v179, v254 op_sel:[0,0,1]
	s_waitcnt lgkmcnt(2)
	v_mfma_scale_f32_32x32x64_f8f6f4 v[98:113], v[222:229], v[138:145], v[98:113], v194, v193 op_sel_hi:[0,0,0]
	ds_read_b128 v[222:225], v185 offset:61440
	ds_read_b128 v[226:229], v186 offset:61440
	v_exp_f32_e32 v0, v70
	v_exp_f32_e32 v177, v71
	v_exp_f32_e32 v179, v72
	v_exp_f32_e32 v254, v73
	v_add_f32_e32 v219, v0, v219
	v_add_f32_e32 v219, v177, v219
	v_cvt_pk_fp8_f32 v251, v0, v177
	v_add_f32_e32 v219, v179, v219
	v_add_f32_e32 v219, v254, v219
	v_cvt_pk_fp8_f32 v251, v179, v254 op_sel:[0,0,1]
	v_exp_f32_e32 v0, v74
	v_exp_f32_e32 v177, v75
	v_exp_f32_e32 v179, v76
	v_exp_f32_e32 v254, v77
	v_add_f32_e32 v219, v0, v219
	v_add_f32_e32 v219, v177, v219
	v_cvt_pk_fp8_f32 v252, v0, v177
	v_add_f32_e32 v219, v179, v219
	v_add_f32_e32 v219, v254, v219
	v_cvt_pk_fp8_f32 v252, v179, v254 op_sel:[0,0,1]
	s_waitcnt lgkmcnt(2)
	v_mfma_scale_f32_32x32x64_f8f6f4 v[114:129], v[90:97], v[130:137], v[114:129], v194, v193 op_sel_hi:[0,0,0]
	v_exp_f32_e32 v0, v78
	v_exp_f32_e32 v177, v79
	v_exp_f32_e32 v179, v80
	v_exp_f32_e32 v254, v81
	v_add_f32_e32 v219, v0, v219
	v_add_f32_e32 v219, v177, v219
	v_cvt_pk_fp8_f32 v253, v0, v177
	v_add_f32_e32 v219, v179, v219
	v_add_f32_e32 v219, v254, v219
	v_cvt_pk_fp8_f32 v253, v179, v254 op_sel:[0,0,1]
	ds_read_b128 v[90:93], v185 offset:8192
	ds_read_b128 v[94:97], v186 offset:8192
	ds_read_b128 v[82:85], v185 offset:10240
	ds_read_b128 v[86:89], v186 offset:10240
	ds_read_b128 v[74:77], v185 offset:12288
	ds_read_b128 v[78:81], v186 offset:12288
	ds_read_b128 v[66:69], v185 offset:14336
	ds_read_b128 v[70:73], v186 offset:14336
	s_waitcnt lgkmcnt(8)
	v_mfma_scale_f32_32x32x64_f8f6f4 v[98:113], v[222:229], v[130:137], v[98:113], v194, v193 op_sel_hi:[0,0,0]
	v_mov_b32_e32 v0, v219
	s_nop 1
	v_permlane32_swap_b32_e32 v219, v0
	v_add_f32_e32 v219, v219, v0
	v_fma_f32 v209, v209, v218, v219
	v_add_u32_e32 v176, 0x2000, v176
	v_add_u32_e32 v178, 0x20000, v178
	s_mov_b64 s[20:21], 0x1000
	v_lshl_add_u64 v[180:181], v[180:181], 0, s[20:21]
	v_max_f32_e32 v177, v114, v115
	v_max3_f32 v177, v177, v116, v117
	v_max3_f32 v177, v177, v118, v119
	v_max3_f32 v177, v177, v120, v121
	v_max3_f32 v177, v177, v122, v123
	v_max3_f32 v177, v177, v124, v125
	v_max3_f32 v177, v177, v126, v127
	v_max3_f32 v177, v177, v128, v129
	s_waitcnt lgkmcnt(6)
	v_mfma_scale_f32_32x32x64_f8f6f4 v[50:65], v[246:253], v[90:97], v[50:65], v194, v194 op_sel_hi:[0,0,0]
	v_max_f32_e32 v0, v98, v99
	v_max3_f32 v0, v0, v100, v101
	v_max3_f32 v0, v0, v102, v103
	s_waitcnt lgkmcnt(4)
	v_mfma_scale_f32_32x32x64_f8f6f4 v[34:49], v[246:253], v[82:89], v[34:49], v194, v194 op_sel_hi:[0,0,0]
	v_max3_f32 v0, v0, v104, v105
	v_max3_f32 v0, v0, v106, v107
	v_max3_f32 v0, v0, v108, v109
	s_waitcnt lgkmcnt(2)
	v_mfma_scale_f32_32x32x64_f8f6f4 v[18:33], v[246:253], v[74:81], v[18:33], v194, v194 op_sel_hi:[0,0,0]
	v_max3_f32 v0, v0, v110, v111
	v_max3_f32 v0, v0, v112, v113
	v_max_f32_e32 v177, v177, v0
	v_mov_b32_e32 v0, v177
	v_mov_b32_e32 v221, 1.0
	s_waitcnt vmcnt(0)
	ds_write_b128 v210, v[158:161]
	ds_write_b128 v211, v[162:165] offset:16384
	ds_write_b128 v212, v[154:157] offset:32768
	s_waitcnt lgkmcnt(3)
	v_mfma_scale_f32_32x32x64_f8f6f4 v[2:17], v[246:253], v[66:73], v[2:17], v194, v194 op_sel_hi:[0,0,0]
	s_waitcnt lgkmcnt(0)
	s_barrier
	v_permlane32_swap_b32_e32 v177, v0
	v_max_f32_e32 v177, v177, v0
	v_cmp_ge_f32_e32 vcc, s90, v177
	s_cmp_eq_u64 vcc, exec
	s_cbranch_scc0 .Lmla_h4_newmax
; __device__ __forceinline__ void finishSM9(f32x16& p0, f32x16& p1, float alpha, float& l_reg, v8i32& p8) {
; #pragma unroll
;   for (int r = 0; r < 16; ++r) { p0[r] = __builtin_amdgcn_exp2f(p0[r]); p1[r] = __builtin_amdgcn_exp2f(p1[r]); }
;   float ps = 0;
; #pragma unroll
;   for (int r = 0; r < 16; ++r) ps += p0[r];
; #pragma unroll
;   for (int r = 0; r < 16; ++r) ps += p1[r];
;   { auto rr = __builtin_amdgcn_permlane32_swap(__float_as_uint(ps), __float_as_uint(ps), false, false);
;     ps = __uint_as_float(rr[0]) + __uint_as_float(rr[1]); }
;   l_reg = l_reg * alpha + ps;
; #pragma unroll
;   for (int g = 0; g < 4; ++g) {
;     int w = __builtin_amdgcn_cvt_pk_fp8_f32(p0[4 * g], p0[4 * g + 1], 0, false); p8[g] = __builtin_amdgcn_cvt_pk_fp8_f32(p0[4 * g + 2], p0[4 * g + 3], w, true);
;     int u = __builtin_amdgcn_cvt_pk_fp8_f32(p1[4 * g], p1[4 * g + 1], 0, false); p8[4 + g] = __builtin_amdgcn_cvt_pk_fp8_f32(p1[4 * g + 2], p1[4 * g + 3], u, true); }
; }
; __device__ __forceinline__ void pv8(f32x16* o, const char* Vt, const v8i32 p8, int r32, int hi) {
;   const int sw = (r32 >> 2) & 3, a0 = r32 * 64 + (((hi * 2) ^ sw) << 4), a1 = r32 * 64 + (((hi * 2 + 1) ^ sw) << 4);
; #pragma unroll
;   for (int d0 = 0; d0 < 4; ++d0) {
;     const v8i32 vf = cat8(*reinterpret_cast<const v4i32*>(Vt + d0 * 2048 + a0), *reinterpret_cast<const v4i32*>(Vt + d0 * 2048 + a1));
;     o[d0] = __builtin_amdgcn_mfma_scale_f32_32x32x64_f8f6f4(p8, vf, o[d0], 0, 0, 0, 127, 0, 127); }
; }
; __device__ __forceinline__ void qkt9(f32x16& p0, f32x16& p1, const char* Kn, const char* Kr, const v8i32* qf, const float init, int r32, int hi) {
; #pragma unroll
;   for (int r = 0; r < 16; ++r) { p0[r] = init; p1[r] = init; }
; #pragma unroll
;   for (int s = 0; s < 2; ++s) { const int c0 = s * 4 + hi * 2;
;     const v8i32 a0 = cat8(*reinterpret_cast<const v4i32*>(Kn + KN8SW(r32, c0)), *reinterpret_cast<const v4i32*>(Kn + KN8SW(r32, c0 + 1)));
;     const v8i32 a1 = cat8(*reinterpret_cast<const v4i32*>(Kn + 4096 + KN8SW(r32, c0)), *reinterpret_cast<const v4i32*>(Kn + 4096 + KN8SW(r32, c0 + 1)));
;     p0 = __builtin_amdgcn_mfma_scale_f32_32x32x64_f8f6f4(a0, qf[s], p0, 0, 0, 0, 127, 0, 124);
;     p1 = __builtin_amdgcn_mfma_scale_f32_32x32x64_f8f6f4(a1, qf[s], p1, 0, 0, 0, 127, 0, 124); }
;   { const int c0 = hi * 2;
.Lmla_h4_cont:
	ds_read_b128 v[82:85], v215 offset:16384
	ds_read_b128 v[86:89], v216 offset:16384
	ds_read_b128 v[222:225], v215 offset:20480
	ds_read_b128 v[226:229], v216 offset:20480
	global_load_dwordx4 v[158:161], v176, s[18:19]
	global_load_dwordx4 v[162:165], v178, s[16:17]
	global_load_dwordx4 v[154:157], v[180:181], off
	v_exp_f32_e32 v0, v114
	v_exp_f32_e32 v177, v115
	v_exp_f32_e32 v179, v116
	v_exp_f32_e32 v254, v117
	v_add_f32_e32 v219, v0, v177
	v_cvt_pk_fp8_f32 v246, v0, v177
	v_add_f32_e32 v219, v179, v219
	v_add_f32_e32 v219, v254, v219
	v_cvt_pk_fp8_f32 v246, v179, v254 op_sel:[0,0,1]
	s_waitcnt lgkmcnt(2)
	v_mfma_scale_f32_32x32x64_f8f6f4 v[82:97], v[82:89], v[146:153], v[230:245], v194, v193 op_sel_hi:[0,0,0]
	v_exp_f32_e32 v0, v118
	v_exp_f32_e32 v177, v119
	v_exp_f32_e32 v179, v120
	v_exp_f32_e32 v254, v121
	v_add_f32_e32 v219, v0, v219
	v_add_f32_e32 v219, v177, v219
	v_cvt_pk_fp8_f32 v247, v0, v177
	v_add_f32_e32 v219, v179, v219
	v_add_f32_e32 v219, v254, v219
	v_cvt_pk_fp8_f32 v247, v179, v254 op_sel:[0,0,1]
	ds_read_b128 v[114:117], v213 offset:16384
	ds_read_b128 v[118:121], v214 offset:16384
	s_waitcnt lgkmcnt(2)
	v_mfma_scale_f32_32x32x64_f8f6f4 v[66:81], v[222:229], v[146:153], v[230:245], v194, v193 op_sel_hi:[0,0,0]
	ds_read_b128 v[222:225], v213 offset:20480
	ds_read_b128 v[226:229], v214 offset:20480
	v_exp_f32_e32 v0, v122
	v_exp_f32_e32 v177, v123
	v_exp_f32_e32 v179, v124
	v_exp_f32_e32 v254, v125
	v_add_f32_e32 v219, v0, v219
	v_add_f32_e32 v219, v177, v219
	v_cvt_pk_fp8_f32 v248, v0, v177
	v_add_f32_e32 v219, v179, v219
	v_add_f32_e32 v219, v254, v219
	v_cvt_pk_fp8_f32 v248, v179, v254 op_sel:[0,0,1]
	v_exp_f32_e32 v0, v126
	v_exp_f32_e32 v177, v127
	v_exp_f32_e32 v179, v128
	v_exp_f32_e32 v254, v129
	v_add_f32_e32 v219, v0, v219
	v_add_f32_e32 v219, v177, v219
	v_cvt_pk_fp8_f32 v249, v0, v177
	v_add_f32_e32 v219, v179, v219
	v_add_f32_e32 v219, v254, v219
	v_cvt_pk_fp8_f32 v249, v179, v254 op_sel:[0,0,1]
	ds_read_b128 v[122:125], v185 offset:32768
	ds_read_b128 v[126:129], v186 offset:32768
	s_waitcnt lgkmcnt(4)
	v_mfma_scale_f32_32x32x64_f8f6f4 v[82:97], v[114:121], v[138:145], v[82:97], v194, v193 op_sel_hi:[0,0,0]
	v_exp_f32_e32 v0, v98
	v_exp_f32_e32 v177, v99
	v_exp_f32_e32 v179, v100
	v_exp_f32_e32 v254, v101
	v_add_f32_e32 v219, v0, v219
	v_add_f32_e32 v219, v177, v219
	v_cvt_pk_fp8_f32 v250, v0, v177
	v_add_f32_e32 v219, v179, v219
	v_add_f32_e32 v219, v254, v219
	v_cvt_pk_fp8_f32 v250, v179, v254 op_sel:[0,0,1]
	s_waitcnt lgkmcnt(2)
	v_mfma_scale_f32_32x32x64_f8f6f4 v[66:81], v[222:229], v[138:145], v[66:81], v194, v193 op_sel_hi:[0,0,0]
	ds_read_b128 v[222:225], v185 offset:34816
	ds_read_b128 v[226:229], v186 offset:34816
	v_exp_f32_e32 v0, v102
	v_exp_f32_e32 v177, v103
	v_exp_f32_e32 v179, v104
	v_exp_f32_e32 v254, v105
	v_add_f32_e32 v219, v0, v219
	v_add_f32_e32 v219, v177, v219
	v_cvt_pk_fp8_f32 v251, v0, v177
	v_add_f32_e32 v219, v179, v219
	v_add_f32_e32 v219, v254, v219
	v_cvt_pk_fp8_f32 v251, v179, v254 op_sel:[0,0,1]
	v_exp_f32_e32 v0, v106
	v_exp_f32_e32 v177, v107
	v_exp_f32_e32 v179, v108
	v_exp_f32_e32 v254, v109
	v_add_f32_e32 v219, v0, v219
	v_add_f32_e32 v219, v177, v219
	v_cvt_pk_fp8_f32 v252, v0, v177
	v_add_f32_e32 v219, v179, v219
	v_add_f32_e32 v219, v254, v219
	v_cvt_pk_fp8_f32 v252, v179, v254 op_sel:[0,0,1]
	s_waitcnt lgkmcnt(2)
	v_mfma_scale_f32_32x32x64_f8f6f4 v[82:97], v[122:129], v[130:137], v[82:97], v194, v193 op_sel_hi:[0,0,0]
	v_exp_f32_e32 v0, v110
	v_exp_f32_e32 v177, v111
	v_exp_f32_e32 v179, v112
	v_exp_f32_e32 v254, v113
	v_add_f32_e32 v219, v0, v219
	v_add_f32_e32 v219, v177, v219
	v_cvt_pk_fp8_f32 v253, v0, v177
	v_add_f32_e32 v219, v179, v219
	v_add_f32_e32 v219, v254, v219
	v_cvt_pk_fp8_f32 v253, v179, v254 op_sel:[0,0,1]
	ds_read_b128 v[122:125], v185 offset:43008
	ds_read_b128 v[126:129], v186 offset:43008
	ds_read_b128 v[114:117], v185 offset:45056
	ds_read_b128 v[118:121], v186 offset:45056
	ds_read_b128 v[106:109], v185 offset:47104
	ds_read_b128 v[110:113], v186 offset:47104
	ds_read_b128 v[98:101], v185 offset:49152
	ds_read_b128 v[102:105], v186 offset:49152
	s_waitcnt lgkmcnt(8)
	v_mfma_scale_f32_32x32x64_f8f6f4 v[66:81], v[222:229], v[130:137], v[66:81], v194, v193 op_sel_hi:[0,0,0]
	v_mov_b32_e32 v0, v219
	s_nop 1
	v_permlane32_swap_b32_e32 v219, v0
	v_add_f32_e32 v219, v219, v0
	v_fma_f32 v209, v209, v221, v219
	v_add_u32_e32 v176, 0x2000, v176
	v_add_u32_e32 v178, 0x20000, v178
	s_mov_b64 s[20:21], 0x1000
	v_lshl_add_u64 v[180:181], v[180:181], 0, s[20:21]
	v_max_f32_e32 v177, v82, v83
	v_max3_f32 v177, v177, v84, v85
	v_max3_f32 v177, v177, v86, v87
	v_max3_f32 v177, v177, v88, v89
	v_max3_f32 v177, v177, v90, v91
	v_max3_f32 v177, v177, v92, v93
	v_max3_f32 v177, v177, v94, v95
	v_max3_f32 v177, v177, v96, v97
	s_waitcnt lgkmcnt(6)
	v_mfma_scale_f32_32x32x64_f8f6f4 v[50:65], v[246:253], v[122:129], v[50:65], v194, v194 op_sel_hi:[0,0,0]
	v_max_f32_e32 v0, v66, v67
	v_max3_f32 v0, v0, v68, v69
	v_max3_f32 v0, v0, v70, v71
	s_waitcnt lgkmcnt(4)
	v_mfma_scale_f32_32x32x64_f8f6f4 v[34:49], v[246:253], v[114:121], v[34:49], v194, v194 op_sel_hi:[0,0,0]
	v_max3_f32 v0, v0, v72, v73
	v_max3_f32 v0, v0, v74, v75
	v_max3_f32 v0, v0, v76, v77
	s_waitcnt lgkmcnt(2)
	v_mfma_scale_f32_32x32x64_f8f6f4 v[18:33], v[246:253], v[106:113], v[18:33], v194, v194 op_sel_hi:[0,0,0]
	v_max3_f32 v0, v0, v78, v79
	v_max3_f32 v0, v0, v80, v81
	v_max_f32_e32 v177, v177, v0
	v_mov_b32_e32 v0, v177
	v_mov_b32_e32 v218, 1.0
	s_waitcnt vmcnt(0)
	ds_write_b128 v210, v[158:161] offset:8192
	ds_write_b128 v211, v[162:165] offset:24576
	ds_write_b128 v212, v[154:157] offset:36864
	s_waitcnt lgkmcnt(3)
	v_mfma_scale_f32_32x32x64_f8f6f4 v[2:17], v[246:253], v[98:105], v[2:17], v194, v194 op_sel_hi:[0,0,0]
	s_waitcnt lgkmcnt(0)
	s_barrier
	v_permlane32_swap_b32_e32 v177, v0
	v_max_f32_e32 v177, v177, v0
	v_cmp_ge_f32_e32 vcc, s90, v177
	s_cmp_eq_u64 vcc, exec
	s_cbranch_scc0 .Lmla_h5_newmax
; __device__ __forceinline__ void finishSM9(f32x16& p0, f32x16& p1, float alpha, float& l_reg, v8i32& p8) {
; #pragma unroll
;   for (int r = 0; r < 16; ++r) { p0[r] = __builtin_amdgcn_exp2f(p0[r]); p1[r] = __builtin_amdgcn_exp2f(p1[r]); }
;   float ps = 0;
; #pragma unroll
;   for (int r = 0; r < 16; ++r) ps += p0[r];
; #pragma unroll
;   for (int r = 0; r < 16; ++r) ps += p1[r];
;   { auto rr = __builtin_amdgcn_permlane32_swap(__float_as_uint(ps), __float_as_uint(ps), false, false);
;     ps = __uint_as_float(rr[0]) + __uint_as_float(rr[1]); }
;   l_reg = l_reg * alpha + ps;
; #pragma unroll
;   for (int g = 0; g < 4; ++g) {
;     int w = __builtin_amdgcn_cvt_pk_fp8_f32(p0[4 * g], p0[4 * g + 1], 0, false); p8[g] = __builtin_amdgcn_cvt_pk_fp8_f32(p0[4 * g + 2], p0[4 * g + 3], w, true);
;     int u = __builtin_amdgcn_cvt_pk_fp8_f32(p1[4 * g], p1[4 * g + 1], 0, false); p8[4 + g] = __builtin_amdgcn_cvt_pk_fp8_f32(p1[4 * g + 2], p1[4 * g + 3], u, true); }
; }
; __device__ __forceinline__ void pv8(f32x16* o, const char* Vt, const v8i32 p8, int r32, int hi) {
;   const int sw = (r32 >> 2) & 3, a0 = r32 * 64 + (((hi * 2) ^ sw) << 4), a1 = r32 * 64 + (((hi * 2 + 1) ^ sw) << 4);
; #pragma unroll
;   for (int d0 = 0; d0 < 4; ++d0) {
;     const v8i32 vf = cat8(*reinterpret_cast<const v4i32*>(Vt + d0 * 2048 + a0), *reinterpret_cast<const v4i32*>(Vt + d0 * 2048 + a1));
;     o[d0] = __builtin_amdgcn_mfma_scale_f32_32x32x64_f8f6f4(p8, vf, o[d0], 0, 0, 0, 127, 0, 127); }
; }
; __device__ __forceinline__ void qkt9(f32x16& p0, f32x16& p1, const char* Kn, const char* Kr, const v8i32* qf, const float init, int r32, int hi) {
; #pragma unroll
;   for (int r = 0; r < 16; ++r) { p0[r] = init; p1[r] = init; }
; #pragma unroll
;   for (int s = 0; s < 2; ++s) { const int c0 = s * 4 + hi * 2;
;     const v8i32 a0 = cat8(*reinterpret_cast<const v4i32*>(Kn + KN8SW(r32, c0)), *reinterpret_cast<const v4i32*>(Kn + KN8SW(r32, c0 + 1)));
;     const v8i32 a1 = cat8(*reinterpret_cast<const v4i32*>(Kn + 4096 + KN8SW(r32, c0)), *reinterpret_cast<const v4i32*>(Kn + 4096 + KN8SW(r32, c0 + 1)));
;     p0 = __builtin_amdgcn_mfma_scale_f32_32x32x64_f8f6f4(a0, qf[s], p0, 0, 0, 0, 127, 0, 124);
;     p1 = __builtin_amdgcn_mfma_scale_f32_32x32x64_f8f6f4(a1, qf[s], p1, 0, 0, 0, 127, 0, 124); }
;   { const int c0 = hi * 2;
.Lmla_h5_cont:
	s_add_i32 s30, s30, 1
	s_cmpk_lt_u32 s30, 42
	s_cbranch_scc1 .LBB0_1321
	ds_read_b128 v[114:117], v215 offset:24576
	ds_read_b128 v[118:121], v216 offset:24576
	ds_read_b128 v[222:225], v215 offset:28672
	ds_read_b128 v[226:229], v216 offset:28672
	global_load_dwordx4 v[158:161], v176, s[18:19]
	global_load_dwordx4 v[162:165], v178, s[16:17]
	global_load_dwordx4 v[154:157], v[180:181], off
	v_exp_f32_e32 v0, v82
	v_exp_f32_e32 v177, v83
	v_exp_f32_e32 v179, v84
	v_exp_f32_e32 v254, v85
	v_add_f32_e32 v219, v0, v177
	v_cvt_pk_fp8_f32 v246, v0, v177
	v_add_f32_e32 v219, v179, v219
	v_add_f32_e32 v219, v254, v219
	v_cvt_pk_fp8_f32 v246, v179, v254 op_sel:[0,0,1]
	s_waitcnt lgkmcnt(2)
	v_mfma_scale_f32_32x32x64_f8f6f4 v[114:129], v[114:121], v[146:153], v[230:245], v194, v193 op_sel_hi:[0,0,0]
	v_exp_f32_e32 v0, v86
	v_exp_f32_e32 v177, v87
	v_exp_f32_e32 v179, v88
	v_exp_f32_e32 v254, v89
	v_add_f32_e32 v219, v0, v219
	v_add_f32_e32 v219, v177, v219
	v_cvt_pk_fp8_f32 v247, v0, v177
	v_add_f32_e32 v219, v179, v219
	v_add_f32_e32 v219, v254, v219
	v_cvt_pk_fp8_f32 v247, v179, v254 op_sel:[0,0,1]
	ds_read_b128 v[82:85], v213 offset:24576
	ds_read_b128 v[86:89], v214 offset:24576
	s_waitcnt lgkmcnt(2)
	v_mfma_scale_f32_32x32x64_f8f6f4 v[98:113], v[222:229], v[146:153], v[230:245], v194, v193 op_sel_hi:[0,0,0]
	ds_read_b128 v[222:225], v213 offset:28672
	ds_read_b128 v[226:229], v214 offset:28672
	v_exp_f32_e32 v0, v90
	v_exp_f32_e32 v177, v91
	v_exp_f32_e32 v179, v92
	v_exp_f32_e32 v254, v93
	v_add_f32_e32 v219, v0, v219
	v_add_f32_e32 v219, v177, v219
	v_cvt_pk_fp8_f32 v248, v0, v177
	v_add_f32_e32 v219, v179, v219
	v_add_f32_e32 v219, v254, v219
	v_cvt_pk_fp8_f32 v248, v179, v254 op_sel:[0,0,1]
	v_exp_f32_e32 v0, v94
	v_exp_f32_e32 v177, v95
	v_exp_f32_e32 v179, v96
	v_exp_f32_e32 v254, v97
	v_add_f32_e32 v219, v0, v219
	v_add_f32_e32 v219, v177, v219
	v_cvt_pk_fp8_f32 v249, v0, v177
	v_add_f32_e32 v219, v179, v219
	v_add_f32_e32 v219, v254, v219
	v_cvt_pk_fp8_f32 v249, v179, v254 op_sel:[0,0,1]
	ds_read_b128 v[90:93], v185 offset:36864
	ds_read_b128 v[94:97], v186 offset:36864
	s_waitcnt lgkmcnt(4)
	v_mfma_scale_f32_32x32x64_f8f6f4 v[114:129], v[82:89], v[138:145], v[114:129], v194, v193 op_sel_hi:[0,0,0]
	v_exp_f32_e32 v0, v66
	v_exp_f32_e32 v177, v67
	v_exp_f32_e32 v179, v68
	v_exp_f32_e32 v254, v69
	v_add_f32_e32 v219, v0, v219
	v_add_f32_e32 v219, v177, v219
	v_cvt_pk_fp8_f32 v250, v0, v177
	v_add_f32_e32 v219, v179, v219
	v_add_f32_e32 v219, v254, v219
	v_cvt_pk_fp8_f32 v250, v179, v254 op_sel:[0,0,1]
	s_waitcnt lgkmcnt(2)
	v_mfma_scale_f32_32x32x64_f8f6f4 v[98:113], v[222:229], v[138:145], v[98:113], v194, v193 op_sel_hi:[0,0,0]
	ds_read_b128 v[222:225], v185 offset:38912
	ds_read_b128 v[226:229], v186 offset:38912
	v_exp_f32_e32 v0, v70
	v_exp_f32_e32 v177, v71
	v_exp_f32_e32 v179, v72
	v_exp_f32_e32 v254, v73
	v_add_f32_e32 v219, v0, v219
	v_add_f32_e32 v219, v177, v219
	v_cvt_pk_fp8_f32 v251, v0, v177
	v_add_f32_e32 v219, v179, v219
	v_add_f32_e32 v219, v254, v219
	v_cvt_pk_fp8_f32 v251, v179, v254 op_sel:[0,0,1]
	v_exp_f32_e32 v0, v74
	v_exp_f32_e32 v177, v75
	v_exp_f32_e32 v179, v76
	v_exp_f32_e32 v254, v77
	v_add_f32_e32 v219, v0, v219
	v_add_f32_e32 v219, v177, v219
	v_cvt_pk_fp8_f32 v252, v0, v177
	v_add_f32_e32 v219, v179, v219
	v_add_f32_e32 v219, v254, v219
	v_cvt_pk_fp8_f32 v252, v179, v254 op_sel:[0,0,1]
	s_waitcnt lgkmcnt(2)
	v_mfma_scale_f32_32x32x64_f8f6f4 v[114:129], v[90:97], v[130:137], v[114:129], v194, v193 op_sel_hi:[0,0,0]
	v_exp_f32_e32 v0, v78
	v_exp_f32_e32 v177, v79
	v_exp_f32_e32 v179, v80
	v_exp_f32_e32 v254, v81
	v_add_f32_e32 v219, v0, v219
	v_add_f32_e32 v219, v177, v219
	v_cvt_pk_fp8_f32 v253, v0, v177
	v_add_f32_e32 v219, v179, v219
	v_add_f32_e32 v219, v254, v219
	v_cvt_pk_fp8_f32 v253, v179, v254 op_sel:[0,0,1]
	ds_read_b128 v[90:93], v185 offset:0
	ds_read_b128 v[94:97], v186 offset:0
	ds_read_b128 v[82:85], v185 offset:2048
	ds_read_b128 v[86:89], v186 offset:2048
	ds_read_b128 v[74:77], v185 offset:4096
	ds_read_b128 v[78:81], v186 offset:4096
	ds_read_b128 v[66:69], v185 offset:6144
	ds_read_b128 v[70:73], v186 offset:6144
	s_waitcnt lgkmcnt(8)
	v_mfma_scale_f32_32x32x64_f8f6f4 v[98:113], v[222:229], v[130:137], v[98:113], v194, v193 op_sel_hi:[0,0,0]
	v_mov_b32_e32 v0, v219
	s_nop 1
	v_permlane32_swap_b32_e32 v219, v0
	v_add_f32_e32 v219, v219, v0
	v_fma_f32 v209, v209, v218, v219
	v_add_u32_e32 v176, 0x2000, v176
	v_add_u32_e32 v178, 0x20000, v178
	s_mov_b64 s[20:21], 0x1000
	v_lshl_add_u64 v[180:181], v[180:181], 0, s[20:21]
	v_max_f32_e32 v177, v114, v115
	v_max3_f32 v177, v177, v116, v117
	v_max3_f32 v177, v177, v118, v119
	v_max3_f32 v177, v177, v120, v121
	v_max3_f32 v177, v177, v122, v123
	v_max3_f32 v177, v177, v124, v125
	v_max3_f32 v177, v177, v126, v127
	v_max3_f32 v177, v177, v128, v129
	s_waitcnt lgkmcnt(6)
	v_mfma_scale_f32_32x32x64_f8f6f4 v[50:65], v[246:253], v[90:97], v[50:65], v194, v194 op_sel_hi:[0,0,0]
	v_max_f32_e32 v0, v98, v99
	v_max3_f32 v0, v0, v100, v101
	v_max3_f32 v0, v0, v102, v103
	s_waitcnt lgkmcnt(4)
	v_mfma_scale_f32_32x32x64_f8f6f4 v[34:49], v[246:253], v[82:89], v[34:49], v194, v194 op_sel_hi:[0,0,0]
	v_max3_f32 v0, v0, v104, v105
	v_max3_f32 v0, v0, v106, v107
	v_max3_f32 v0, v0, v108, v109
	s_waitcnt lgkmcnt(2)
	v_mfma_scale_f32_32x32x64_f8f6f4 v[18:33], v[246:253], v[74:81], v[18:33], v194, v194 op_sel_hi:[0,0,0]
	v_max3_f32 v0, v0, v110, v111
	v_max3_f32 v0, v0, v112, v113
	v_max_f32_e32 v177, v177, v0
	v_mov_b32_e32 v0, v177
	v_mov_b32_e32 v221, 1.0
	s_waitcnt vmcnt(0)
	ds_write_b128 v210, v[158:161] offset:43008
	ds_write_b128 v211, v[162:165] offset:51200
	ds_write_b128 v212, v[154:157] offset:59392
	s_waitcnt lgkmcnt(3)
	v_mfma_scale_f32_32x32x64_f8f6f4 v[2:17], v[246:253], v[66:73], v[2:17], v194, v194 op_sel_hi:[0,0,0]
	s_waitcnt lgkmcnt(0)
	s_barrier
	v_permlane32_swap_b32_e32 v177, v0
	v_max_f32_e32 v177, v177, v0
	v_cmp_ge_f32_e32 vcc, s90, v177
	s_cmp_eq_u64 vcc, exec
	s_cbranch_scc0 .Lmla_p0_newmax

; __device__ __forceinline__ void finishSM9(f32x16& p0, f32x16& p1, float alpha, float& l_reg, v8i32& p8) {
; #pragma unroll
;   for (int r = 0; r < 16; ++r) { p0[r] = __builtin_amdgcn_exp2f(p0[r]); p1[r] = __builtin_amdgcn_exp2f(p1[r]); }
;   float ps = 0;
; #pragma unroll
;   for (int r = 0; r < 16; ++r) ps += p0[r];
; #pragma unroll
;   for (int r = 0; r < 16; ++r) ps += p1[r];
;   { auto rr = __builtin_amdgcn_permlane32_swap(__float_as_uint(ps), __float_as_uint(ps), false, false);
;     ps = __uint_as_float(rr[0]) + __uint_as_float(rr[1]); }
;   l_reg = l_reg * alpha + ps;
; #pragma unroll
;   for (int g = 0; g < 4; ++g) {
;     int w = __builtin_amdgcn_cvt_pk_fp8_f32(p0[4 * g], p0[4 * g + 1], 0, false); p8[g] = __builtin_amdgcn_cvt_pk_fp8_f32(p0[4 * g + 2], p0[4 * g + 3], w, true);
;     int u = __builtin_amdgcn_cvt_pk_fp8_f32(p1[4 * g], p1[4 * g + 1], 0, false); p8[4 + g] = __builtin_amdgcn_cvt_pk_fp8_f32(p1[4 * g + 2], p1[4 * g + 3], u, true); }
; }
; __device__ __forceinline__ void pv8(f32x16* o, const char* Vt, const v8i32 p8, int r32, int hi) {
;   const int sw = (r32 >> 2) & 3, a0 = r32 * 64 + (((hi * 2) ^ sw) << 4), a1 = r32 * 64 + (((hi * 2 + 1) ^ sw) << 4);
; #pragma unroll
;   for (int d0 = 0; d0 < 4; ++d0) {
;     const v8i32 vf = cat8(*reinterpret_cast<const v4i32*>(Vt + d0 * 2048 + a0), *reinterpret_cast<const v4i32*>(Vt + d0 * 2048 + a1));
;     o[d0] = __builtin_amdgcn_mfma_scale_f32_32x32x64_f8f6f4(p8, vf, o[d0], 0, 0, 0, 127, 0, 127); }
; }
; __device__ __forceinline__ void qkt9(f32x16& p0, f32x16& p1, const char* Kn, const char* Kr, const v8i32* qf, const float init, int r32, int hi) {
; #pragma unroll
;   for (int r = 0; r < 16; ++r) { p0[r] = init; p1[r] = init; }
; #pragma unroll
;   for (int s = 0; s < 2; ++s) { const int c0 = s * 4 + hi * 2;
;     const v8i32 a0 = cat8(*reinterpret_cast<const v4i32*>(Kn + KN8SW(r32, c0)), *reinterpret_cast<const v4i32*>(Kn + KN8SW(r32, c0 + 1)));
;     const v8i32 a1 = cat8(*reinterpret_cast<const v4i32*>(Kn + 4096 + KN8SW(r32, c0)), *reinterpret_cast<const v4i32*>(Kn + 4096 + KN8SW(r32, c0 + 1)));
;     p0 = __builtin_amdgcn_mfma_scale_f32_32x32x64_f8f6f4(a0, qf[s], p0, 0, 0, 0, 127, 0, 124);
;     p1 = __builtin_amdgcn_mfma_scale_f32_32x32x64_f8f6f4(a1, qf[s], p1, 0, 0, 0, 127, 0, 124); }
;   { const int c0 = hi * 2;
.Lmla_stag_loop:
	ds_read_b128 v[114:117], v215 offset:24576
	ds_read_b128 v[118:121], v216 offset:24576
	ds_read_b128 v[222:225], v215 offset:28672
	ds_read_b128 v[226:229], v216 offset:28672
	v_exp_f32_e32 v0, v82
	v_exp_f32_e32 v177, v83
	v_exp_f32_e32 v179, v84
	v_exp_f32_e32 v254, v85
	v_add_f32_e32 v219, v0, v177
	v_cvt_pk_fp8_f32 v246, v0, v177
	v_add_f32_e32 v219, v179, v219
	v_add_f32_e32 v219, v254, v219
	v_cvt_pk_fp8_f32 v246, v179, v254 op_sel:[0,0,1]
	s_waitcnt lgkmcnt(2)
	v_mfma_scale_f32_32x32x64_f8f6f4 v[114:129], v[114:121], v[146:153], v[230:245], v194, v193 op_sel_hi:[0,0,0]
	v_exp_f32_e32 v0, v86
	v_exp_f32_e32 v177, v87
	v_exp_f32_e32 v179, v88
	v_exp_f32_e32 v254, v89
	v_add_f32_e32 v219, v0, v219
	v_add_f32_e32 v219, v177, v219
	v_cvt_pk_fp8_f32 v247, v0, v177
	v_add_f32_e32 v219, v179, v219
	v_add_f32_e32 v219, v254, v219
	v_cvt_pk_fp8_f32 v247, v179, v254 op_sel:[0,0,1]
	ds_read_b128 v[82:85], v213 offset:24576
	ds_read_b128 v[86:89], v214 offset:24576
	s_waitcnt lgkmcnt(2)
	v_mfma_scale_f32_32x32x64_f8f6f4 v[98:113], v[222:229], v[146:153], v[230:245], v194, v193 op_sel_hi:[0,0,0]
	ds_read_b128 v[222:225], v213 offset:28672
	ds_read_b128 v[226:229], v214 offset:28672
	v_exp_f32_e32 v0, v90
	v_exp_f32_e32 v177, v91
	v_exp_f32_e32 v179, v92
	v_exp_f32_e32 v254, v93
	v_add_f32_e32 v219, v0, v219
	v_add_f32_e32 v219, v177, v219
	v_cvt_pk_fp8_f32 v248, v0, v177
	v_add_f32_e32 v219, v179, v219
	v_add_f32_e32 v219, v254, v219
	v_cvt_pk_fp8_f32 v248, v179, v254 op_sel:[0,0,1]
	v_exp_f32_e32 v0, v94
	v_exp_f32_e32 v177, v95
	v_exp_f32_e32 v179, v96
	v_exp_f32_e32 v254, v97
	v_add_f32_e32 v219, v0, v219
	v_add_f32_e32 v219, v177, v219
	v_cvt_pk_fp8_f32 v249, v0, v177
	v_add_f32_e32 v219, v179, v219
	v_add_f32_e32 v219, v254, v219
	v_cvt_pk_fp8_f32 v249, v179, v254 op_sel:[0,0,1]
	ds_read_b128 v[90:93], v185 offset:36864
	ds_read_b128 v[94:97], v186 offset:36864
	s_waitcnt lgkmcnt(4)
	v_mfma_scale_f32_32x32x64_f8f6f4 v[114:129], v[82:89], v[138:145], v[114:129], v194, v193 op_sel_hi:[0,0,0]
	v_exp_f32_e32 v0, v66
	v_exp_f32_e32 v177, v67
	v_exp_f32_e32 v179, v68
	v_exp_f32_e32 v254, v69
	v_add_f32_e32 v219, v0, v219
	v_add_f32_e32 v219, v177, v219
	v_cvt_pk_fp8_f32 v250, v0, v177
	v_add_f32_e32 v219, v179, v219
	v_add_f32_e32 v219, v254, v219
	v_cvt_pk_fp8_f32 v250, v179, v254 op_sel:[0,0,1]
	s_waitcnt lgkmcnt(2)
	v_mfma_scale_f32_32x32x64_f8f6f4 v[98:113], v[222:229], v[138:145], v[98:113], v194, v193 op_sel_hi:[0,0,0]
	ds_read_b128 v[222:225], v185 offset:38912
	ds_read_b128 v[226:229], v186 offset:38912
	v_exp_f32_e32 v0, v70
	v_exp_f32_e32 v177, v71
	v_exp_f32_e32 v179, v72
	v_exp_f32_e32 v254, v73
	v_add_f32_e32 v219, v0, v219
	v_add_f32_e32 v219, v177, v219
	v_cvt_pk_fp8_f32 v251, v0, v177
	v_add_f32_e32 v219, v179, v219
	v_add_f32_e32 v219, v254, v219
	v_cvt_pk_fp8_f32 v251, v179, v254 op_sel:[0,0,1]
	v_exp_f32_e32 v0, v74
	v_exp_f32_e32 v177, v75
	v_exp_f32_e32 v179, v76
	v_exp_f32_e32 v254, v77
	v_add_f32_e32 v219, v0, v219
	v_add_f32_e32 v219, v177, v219
	v_cvt_pk_fp8_f32 v252, v0, v177
	v_add_f32_e32 v219, v179, v219
	v_add_f32_e32 v219, v254, v219
	v_cvt_pk_fp8_f32 v252, v179, v254 op_sel:[0,0,1]
	s_waitcnt lgkmcnt(2)
	v_mfma_scale_f32_32x32x64_f8f6f4 v[114:129], v[90:97], v[130:137], v[114:129], v194, v193 op_sel_hi:[0,0,0]
	v_exp_f32_e32 v0, v78
	v_exp_f32_e32 v177, v79
	v_exp_f32_e32 v179, v80
	v_exp_f32_e32 v254, v81
	v_add_f32_e32 v219, v0, v219
	v_add_f32_e32 v219, v177, v219
	v_cvt_pk_fp8_f32 v253, v0, v177
	v_add_f32_e32 v219, v179, v219
	v_add_f32_e32 v219, v254, v219
	v_cvt_pk_fp8_f32 v253, v179, v254 op_sel:[0,0,1]
	ds_read_b128 v[90:93], v185 offset:0
	ds_read_b128 v[94:97], v186 offset:0
	ds_read_b128 v[82:85], v185 offset:2048
	ds_read_b128 v[86:89], v186 offset:2048
	ds_read_b128 v[74:77], v185 offset:4096
	ds_read_b128 v[78:81], v186 offset:4096
	ds_read_b128 v[66:69], v185 offset:6144
	ds_read_b128 v[70:73], v186 offset:6144
	s_waitcnt lgkmcnt(8)
	v_mfma_scale_f32_32x32x64_f8f6f4 v[98:113], v[222:229], v[130:137], v[98:113], v194, v193 op_sel_hi:[0,0,0]
	v_mov_b32_e32 v0, v219
	s_nop 1
	v_permlane32_swap_b32_e32 v219, v0
	v_add_f32_e32 v219, v219, v0
	v_fma_f32 v209, v209, v218, v219
	v_max_f32_e32 v177, v114, v115
	v_max3_f32 v177, v177, v116, v117
	v_max3_f32 v177, v177, v118, v119
	v_max3_f32 v177, v177, v120, v121
	v_max3_f32 v177, v177, v122, v123
	v_max3_f32 v177, v177, v124, v125
	v_max3_f32 v177, v177, v126, v127
	v_max3_f32 v177, v177, v128, v129
	s_waitcnt lgkmcnt(6)
	v_mfma_scale_f32_32x32x64_f8f6f4 v[50:65], v[246:253], v[90:97], v[50:65], v194, v194 op_sel_hi:[0,0,0]
	s_waitcnt vmcnt(0)
	ds_write_b128 v210, v[158:161] offset:43008
	ds_write_b128 v211, v[162:165] offset:51200
	s_waitcnt lgkmcnt(6)
	v_mfma_scale_f32_32x32x64_f8f6f4 v[34:49], v[246:253], v[82:89], v[34:49], v194, v194 op_sel_hi:[0,0,0]
	s_waitcnt lgkmcnt(0)
	s_barrier
	v_max_f32_e32 v0, v98, v99
	v_max3_f32 v0, v0, v100, v101
	v_max3_f32 v0, v0, v102, v103
	v_max3_f32 v0, v0, v104, v105
	s_waitcnt lgkmcnt(2)
	v_mfma_scale_f32_32x32x64_f8f6f4 v[18:33], v[246:253], v[74:81], v[18:33], v194, v194 op_sel_hi:[0,0,0]
	global_load_dwordx4 v[158:161], v176, s[18:19]
	global_load_dwordx4 v[162:165], v178, s[16:17]
	v_add_u32_e32 v176, 0x2000, v176
	v_add_u32_e32 v178, 0x20000, v178
	v_max3_f32 v0, v0, v106, v107
	v_max3_f32 v0, v0, v108, v109
	v_max3_f32 v0, v0, v110, v111
	v_max3_f32 v0, v0, v112, v113
	s_waitcnt lgkmcnt(0)
	v_mfma_scale_f32_32x32x64_f8f6f4 v[2:17], v[246:253], v[66:73], v[2:17], v194, v194 op_sel_hi:[0,0,0]
	v_max_f32_e32 v177, v177, v0
	v_mov_b32_e32 v0, v177
	v_mov_b32_e32 v221, 1.0
	s_nop 0
	v_permlane32_swap_b32_e32 v177, v0
	v_max_f32_e32 v177, v177, v0
	v_cmp_ge_f32_e32 vcc, s90, v177
	s_cmp_eq_u64 vcc, exec
	s_cbranch_scc0 .Lmla_s0_newmax
; __device__ __forceinline__ void finishSM9(f32x16& p0, f32x16& p1, float alpha, float& l_reg, v8i32& p8) {
; #pragma unroll
;   for (int r = 0; r < 16; ++r) { p0[r] = __builtin_amdgcn_exp2f(p0[r]); p1[r] = __builtin_amdgcn_exp2f(p1[r]); }
;   float ps = 0;
; #pragma unroll
;   for (int r = 0; r < 16; ++r) ps += p0[r];
; #pragma unroll
;   for (int r = 0; r < 16; ++r) ps += p1[r];
;   { auto rr = __builtin_amdgcn_permlane32_swap(__float_as_uint(ps), __float_as_uint(ps), false, false);
;     ps = __uint_as_float(rr[0]) + __uint_as_float(rr[1]); }
;   l_reg = l_reg * alpha + ps;
; #pragma unroll
;   for (int g = 0; g < 4; ++g) {
;     int w = __builtin_amdgcn_cvt_pk_fp8_f32(p0[4 * g], p0[4 * g + 1], 0, false); p8[g] = __builtin_amdgcn_cvt_pk_fp8_f32(p0[4 * g + 2], p0[4 * g + 3], w, true);
;     int u = __builtin_amdgcn_cvt_pk_fp8_f32(p1[4 * g], p1[4 * g + 1], 0, false); p8[4 + g] = __builtin_amdgcn_cvt_pk_fp8_f32(p1[4 * g + 2], p1[4 * g + 3], u, true); }
; }
; __device__ __forceinline__ void pv8(f32x16* o, const char* Vt, const v8i32 p8, int r32, int hi) {
;   const int sw = (r32 >> 2) & 3, a0 = r32 * 64 + (((hi * 2) ^ sw) << 4), a1 = r32 * 64 + (((hi * 2 + 1) ^ sw) << 4);
; #pragma unroll
;   for (int d0 = 0; d0 < 4; ++d0) {
;     const v8i32 vf = cat8(*reinterpret_cast<const v4i32*>(Vt + d0 * 2048 + a0), *reinterpret_cast<const v4i32*>(Vt + d0 * 2048 + a1));
;     o[d0] = __builtin_amdgcn_mfma_scale_f32_32x32x64_f8f6f4(p8, vf, o[d0], 0, 0, 0, 127, 0, 127); }
; }
; __device__ __forceinline__ void qkt9(f32x16& p0, f32x16& p1, const char* Kn, const char* Kr, const v8i32* qf, const float init, int r32, int hi) {
; #pragma unroll
;   for (int r = 0; r < 16; ++r) { p0[r] = init; p1[r] = init; }
; #pragma unroll
;   for (int s = 0; s < 2; ++s) { const int c0 = s * 4 + hi * 2;
;     const v8i32 a0 = cat8(*reinterpret_cast<const v4i32*>(Kn + KN8SW(r32, c0)), *reinterpret_cast<const v4i32*>(Kn + KN8SW(r32, c0 + 1)));
;     const v8i32 a1 = cat8(*reinterpret_cast<const v4i32*>(Kn + 4096 + KN8SW(r32, c0)), *reinterpret_cast<const v4i32*>(Kn + 4096 + KN8SW(r32, c0 + 1)));
;     p0 = __builtin_amdgcn_mfma_scale_f32_32x32x64_f8f6f4(a0, qf[s], p0, 0, 0, 0, 127, 0, 124);
;     p1 = __builtin_amdgcn_mfma_scale_f32_32x32x64_f8f6f4(a1, qf[s], p1, 0, 0, 0, 127, 0, 124); }
;   { const int c0 = hi * 2;
.Lmla_s0_cont:
	ds_read_b128 v[82:85], v215 offset:51200
	ds_read_b128 v[86:89], v216 offset:51200
	ds_read_b128 v[222:225], v215 offset:55296
	ds_read_b128 v[226:229], v216 offset:55296
	v_exp_f32_e32 v0, v114
	v_exp_f32_e32 v177, v115
	v_exp_f32_e32 v179, v116
	v_exp_f32_e32 v254, v117
	v_add_f32_e32 v219, v0, v177
	v_cvt_pk_fp8_f32 v246, v0, v177
	v_add_f32_e32 v219, v179, v219
	v_add_f32_e32 v219, v254, v219
	v_cvt_pk_fp8_f32 v246, v179, v254 op_sel:[0,0,1]
	s_waitcnt lgkmcnt(2)
	v_mfma_scale_f32_32x32x64_f8f6f4 v[82:97], v[82:89], v[146:153], v[230:245], v194, v193 op_sel_hi:[0,0,0]
	v_exp_f32_e32 v0, v118
	v_exp_f32_e32 v177, v119
	v_exp_f32_e32 v179, v120
	v_exp_f32_e32 v254, v121
	v_add_f32_e32 v219, v0, v219
	v_add_f32_e32 v219, v177, v219
	v_cvt_pk_fp8_f32 v247, v0, v177
	v_add_f32_e32 v219, v179, v219
	v_add_f32_e32 v219, v254, v219
	v_cvt_pk_fp8_f32 v247, v179, v254 op_sel:[0,0,1]
	ds_read_b128 v[114:117], v213 offset:51200
	ds_read_b128 v[118:121], v214 offset:51200
	s_waitcnt lgkmcnt(2)
	v_mfma_scale_f32_32x32x64_f8f6f4 v[66:81], v[222:229], v[146:153], v[230:245], v194, v193 op_sel_hi:[0,0,0]
	ds_read_b128 v[222:225], v213 offset:55296
	ds_read_b128 v[226:229], v214 offset:55296
	v_exp_f32_e32 v0, v122
	v_exp_f32_e32 v177, v123
	v_exp_f32_e32 v179, v124
	v_exp_f32_e32 v254, v125
	v_add_f32_e32 v219, v0, v219
	v_add_f32_e32 v219, v177, v219
	v_cvt_pk_fp8_f32 v248, v0, v177
	v_add_f32_e32 v219, v179, v219
	v_add_f32_e32 v219, v254, v219
	v_cvt_pk_fp8_f32 v248, v179, v254 op_sel:[0,0,1]
	v_exp_f32_e32 v0, v126
	v_exp_f32_e32 v177, v127
	v_exp_f32_e32 v179, v128
	v_exp_f32_e32 v254, v129
	v_add_f32_e32 v219, v0, v219
	v_add_f32_e32 v219, v177, v219
	v_cvt_pk_fp8_f32 v249, v0, v177
	v_add_f32_e32 v219, v179, v219
	v_add_f32_e32 v219, v254, v219
	v_cvt_pk_fp8_f32 v249, v179, v254 op_sel:[0,0,1]
	ds_read_b128 v[122:125], v185 offset:59392
	ds_read_b128 v[126:129], v186 offset:59392
	s_waitcnt lgkmcnt(4)
	v_mfma_scale_f32_32x32x64_f8f6f4 v[82:97], v[114:121], v[138:145], v[82:97], v194, v193 op_sel_hi:[0,0,0]
	v_exp_f32_e32 v0, v98
	v_exp_f32_e32 v177, v99
	v_exp_f32_e32 v179, v100
	v_exp_f32_e32 v254, v101
	v_add_f32_e32 v219, v0, v219
	v_add_f32_e32 v219, v177, v219
	v_cvt_pk_fp8_f32 v250, v0, v177
	v_add_f32_e32 v219, v179, v219
	v_add_f32_e32 v219, v254, v219
	v_cvt_pk_fp8_f32 v250, v179, v254 op_sel:[0,0,1]
	s_waitcnt lgkmcnt(2)
	v_mfma_scale_f32_32x32x64_f8f6f4 v[66:81], v[222:229], v[138:145], v[66:81], v194, v193 op_sel_hi:[0,0,0]
	ds_read_b128 v[222:225], v185 offset:61440
	ds_read_b128 v[226:229], v186 offset:61440
	v_exp_f32_e32 v0, v102
	v_exp_f32_e32 v177, v103
	v_exp_f32_e32 v179, v104
	v_exp_f32_e32 v254, v105
	v_add_f32_e32 v219, v0, v219
	v_add_f32_e32 v219, v177, v219
	v_cvt_pk_fp8_f32 v251, v0, v177
	v_add_f32_e32 v219, v179, v219
	v_add_f32_e32 v219, v254, v219
	v_cvt_pk_fp8_f32 v251, v179, v254 op_sel:[0,0,1]
	v_exp_f32_e32 v0, v106
	v_exp_f32_e32 v177, v107
	v_exp_f32_e32 v179, v108
	v_exp_f32_e32 v254, v109
	v_add_f32_e32 v219, v0, v219
	v_add_f32_e32 v219, v177, v219
	v_cvt_pk_fp8_f32 v252, v0, v177
	v_add_f32_e32 v219, v179, v219
	v_add_f32_e32 v219, v254, v219
	v_cvt_pk_fp8_f32 v252, v179, v254 op_sel:[0,0,1]
	s_waitcnt lgkmcnt(2)
	v_mfma_scale_f32_32x32x64_f8f6f4 v[82:97], v[122:129], v[130:137], v[82:97], v194, v193 op_sel_hi:[0,0,0]
	v_exp_f32_e32 v0, v110
	v_exp_f32_e32 v177, v111
	v_exp_f32_e32 v179, v112
	v_exp_f32_e32 v254, v113
	v_add_f32_e32 v219, v0, v219
	v_add_f32_e32 v219, v177, v219
	v_cvt_pk_fp8_f32 v253, v0, v177
	v_add_f32_e32 v219, v179, v219
	v_add_f32_e32 v219, v254, v219
	v_cvt_pk_fp8_f32 v253, v179, v254 op_sel:[0,0,1]
	ds_read_b128 v[122:125], v185 offset:8192
	ds_read_b128 v[126:129], v186 offset:8192
	ds_read_b128 v[114:117], v185 offset:10240
	ds_read_b128 v[118:121], v186 offset:10240
	ds_read_b128 v[106:109], v185 offset:12288
	ds_read_b128 v[110:113], v186 offset:12288
	ds_read_b128 v[98:101], v185 offset:14336
	ds_read_b128 v[102:105], v186 offset:14336
	s_waitcnt lgkmcnt(8)
	v_mfma_scale_f32_32x32x64_f8f6f4 v[66:81], v[222:229], v[130:137], v[66:81], v194, v193 op_sel_hi:[0,0,0]
	v_mov_b32_e32 v0, v219
	s_nop 1
	v_permlane32_swap_b32_e32 v219, v0
	v_add_f32_e32 v219, v219, v0
	v_fma_f32 v209, v209, v221, v219
	v_max_f32_e32 v177, v82, v83
	v_max3_f32 v177, v177, v84, v85
	v_max3_f32 v177, v177, v86, v87
	v_max3_f32 v177, v177, v88, v89
	v_max3_f32 v177, v177, v90, v91
	v_max3_f32 v177, v177, v92, v93
	v_max3_f32 v177, v177, v94, v95
	v_max3_f32 v177, v177, v96, v97
	s_waitcnt lgkmcnt(6)
	v_mfma_scale_f32_32x32x64_f8f6f4 v[50:65], v[246:253], v[122:129], v[50:65], v194, v194 op_sel_hi:[0,0,0]
	s_waitcnt vmcnt(0)
	ds_write_b128 v210, v[158:161]
	ds_write_b128 v211, v[162:165] offset:16384
	s_waitcnt lgkmcnt(6)
	v_mfma_scale_f32_32x32x64_f8f6f4 v[34:49], v[246:253], v[114:121], v[34:49], v194, v194 op_sel_hi:[0,0,0]
	s_waitcnt lgkmcnt(0)
	s_barrier
	v_max_f32_e32 v0, v66, v67
	v_max3_f32 v0, v0, v68, v69
	v_max3_f32 v0, v0, v70, v71
	v_max3_f32 v0, v0, v72, v73
	s_waitcnt lgkmcnt(2)
	v_mfma_scale_f32_32x32x64_f8f6f4 v[18:33], v[246:253], v[106:113], v[18:33], v194, v194 op_sel_hi:[0,0,0]
	global_load_dwordx4 v[158:161], v176, s[18:19]
	global_load_dwordx4 v[162:165], v178, s[16:17]
	v_add_u32_e32 v176, 0x2000, v176
	v_add_u32_e32 v178, 0x20000, v178
	v_max3_f32 v0, v0, v74, v75
	v_max3_f32 v0, v0, v76, v77
	v_max3_f32 v0, v0, v78, v79
	v_max3_f32 v0, v0, v80, v81
	s_waitcnt lgkmcnt(0)
	v_mfma_scale_f32_32x32x64_f8f6f4 v[2:17], v[246:253], v[98:105], v[2:17], v194, v194 op_sel_hi:[0,0,0]
	v_max_f32_e32 v177, v177, v0
	v_mov_b32_e32 v0, v177
	v_mov_b32_e32 v218, 1.0
	s_nop 0
	v_permlane32_swap_b32_e32 v177, v0
	v_max_f32_e32 v177, v177, v0
	v_cmp_ge_f32_e32 vcc, s90, v177
	s_cmp_eq_u64 vcc, exec
	s_cbranch_scc0 .Lmla_s1_newmax
; __device__ __forceinline__ void finishSM9(f32x16& p0, f32x16& p1, float alpha, float& l_reg, v8i32& p8) {
; #pragma unroll
;   for (int r = 0; r < 16; ++r) { p0[r] = __builtin_amdgcn_exp2f(p0[r]); p1[r] = __builtin_amdgcn_exp2f(p1[r]); }
;   float ps = 0;
; #pragma unroll
;   for (int r = 0; r < 16; ++r) ps += p0[r];
; #pragma unroll
;   for (int r = 0; r < 16; ++r) ps += p1[r];
;   { auto rr = __builtin_amdgcn_permlane32_swap(__float_as_uint(ps), __float_as_uint(ps), false, false);
;     ps = __uint_as_float(rr[0]) + __uint_as_float(rr[1]); }
;   l_reg = l_reg * alpha + ps;
; #pragma unroll
;   for (int g = 0; g < 4; ++g) {
;     int w = __builtin_amdgcn_cvt_pk_fp8_f32(p0[4 * g], p0[4 * g + 1], 0, false); p8[g] = __builtin_amdgcn_cvt_pk_fp8_f32(p0[4 * g + 2], p0[4 * g + 3], w, true);
;     int u = __builtin_amdgcn_cvt_pk_fp8_f32(p1[4 * g], p1[4 * g + 1], 0, false); p8[4 + g] = __builtin_amdgcn_cvt_pk_fp8_f32(p1[4 * g + 2], p1[4 * g + 3], u, true); }
; }
; __device__ __forceinline__ void pv8(f32x16* o, const char* Vt, const v8i32 p8, int r32, int hi) {
;   const int sw = (r32 >> 2) & 3, a0 = r32 * 64 + (((hi * 2) ^ sw) << 4), a1 = r32 * 64 + (((hi * 2 + 1) ^ sw) << 4);
; #pragma unroll
;   for (int d0 = 0; d0 < 4; ++d0) {
;     const v8i32 vf = cat8(*reinterpret_cast<const v4i32*>(Vt + d0 * 2048 + a0), *reinterpret_cast<const v4i32*>(Vt + d0 * 2048 + a1));
;     o[d0] = __builtin_amdgcn_mfma_scale_f32_32x32x64_f8f6f4(p8, vf, o[d0], 0, 0, 0, 127, 0, 127); }
; }
; __device__ __forceinline__ void qkt9(f32x16& p0, f32x16& p1, const char* Kn, const char* Kr, const v8i32* qf, const float init, int r32, int hi) {
; #pragma unroll
;   for (int r = 0; r < 16; ++r) { p0[r] = init; p1[r] = init; }
; #pragma unroll
;   for (int s = 0; s < 2; ++s) { const int c0 = s * 4 + hi * 2;
;     const v8i32 a0 = cat8(*reinterpret_cast<const v4i32*>(Kn + KN8SW(r32, c0)), *reinterpret_cast<const v4i32*>(Kn + KN8SW(r32, c0 + 1)));
;     const v8i32 a1 = cat8(*reinterpret_cast<const v4i32*>(Kn + 4096 + KN8SW(r32, c0)), *reinterpret_cast<const v4i32*>(Kn + 4096 + KN8SW(r32, c0 + 1)));
;     p0 = __builtin_amdgcn_mfma_scale_f32_32x32x64_f8f6f4(a0, qf[s], p0, 0, 0, 0, 127, 0, 124);
;     p1 = __builtin_amdgcn_mfma_scale_f32_32x32x64_f8f6f4(a1, qf[s], p1, 0, 0, 0, 127, 0, 124); }
;   { const int c0 = hi * 2;
.Lmla_s1_cont:
	ds_read_b128 v[114:117], v215 offset:16384
	ds_read_b128 v[118:121], v216 offset:16384
	ds_read_b128 v[222:225], v215 offset:20480
	ds_read_b128 v[226:229], v216 offset:20480
	v_exp_f32_e32 v0, v82
	v_exp_f32_e32 v177, v83
	v_exp_f32_e32 v179, v84
	v_exp_f32_e32 v254, v85
	v_add_f32_e32 v219, v0, v177
	v_cvt_pk_fp8_f32 v246, v0, v177
	v_add_f32_e32 v219, v179, v219
	v_add_f32_e32 v219, v254, v219
	v_cvt_pk_fp8_f32 v246, v179, v254 op_sel:[0,0,1]
	s_waitcnt lgkmcnt(2)
	v_mfma_scale_f32_32x32x64_f8f6f4 v[114:129], v[114:121], v[146:153], v[230:245], v194, v193 op_sel_hi:[0,0,0]
	v_exp_f32_e32 v0, v86
	v_exp_f32_e32 v177, v87
	v_exp_f32_e32 v179, v88
	v_exp_f32_e32 v254, v89
	v_add_f32_e32 v219, v0, v219
	v_add_f32_e32 v219, v177, v219
	v_cvt_pk_fp8_f32 v247, v0, v177
	v_add_f32_e32 v219, v179, v219
	v_add_f32_e32 v219, v254, v219
	v_cvt_pk_fp8_f32 v247, v179, v254 op_sel:[0,0,1]
	ds_read_b128 v[82:85], v213 offset:16384
	ds_read_b128 v[86:89], v214 offset:16384
	s_waitcnt lgkmcnt(2)
	v_mfma_scale_f32_32x32x64_f8f6f4 v[98:113], v[222:229], v[146:153], v[230:245], v194, v193 op_sel_hi:[0,0,0]
	ds_read_b128 v[222:225], v213 offset:20480
	ds_read_b128 v[226:229], v214 offset:20480
	v_exp_f32_e32 v0, v90
	v_exp_f32_e32 v177, v91
	v_exp_f32_e32 v179, v92
	v_exp_f32_e32 v254, v93
	v_add_f32_e32 v219, v0, v219
	v_add_f32_e32 v219, v177, v219
	v_cvt_pk_fp8_f32 v248, v0, v177
	v_add_f32_e32 v219, v179, v219
	v_add_f32_e32 v219, v254, v219
	v_cvt_pk_fp8_f32 v248, v179, v254 op_sel:[0,0,1]
	v_exp_f32_e32 v0, v94
	v_exp_f32_e32 v177, v95
	v_exp_f32_e32 v179, v96
	v_exp_f32_e32 v254, v97
	v_add_f32_e32 v219, v0, v219
	v_add_f32_e32 v219, v177, v219
	v_cvt_pk_fp8_f32 v249, v0, v177
	v_add_f32_e32 v219, v179, v219
	v_add_f32_e32 v219, v254, v219
	v_cvt_pk_fp8_f32 v249, v179, v254 op_sel:[0,0,1]
	ds_read_b128 v[90:93], v185 offset:32768
	ds_read_b128 v[94:97], v186 offset:32768
	s_waitcnt lgkmcnt(4)
	v_mfma_scale_f32_32x32x64_f8f6f4 v[114:129], v[82:89], v[138:145], v[114:129], v194, v193 op_sel_hi:[0,0,0]
	v_exp_f32_e32 v0, v66
	v_exp_f32_e32 v177, v67
	v_exp_f32_e32 v179, v68
	v_exp_f32_e32 v254, v69
	v_add_f32_e32 v219, v0, v219
	v_add_f32_e32 v219, v177, v219
	v_cvt_pk_fp8_f32 v250, v0, v177
	v_add_f32_e32 v219, v179, v219
	v_add_f32_e32 v219, v254, v219
	v_cvt_pk_fp8_f32 v250, v179, v254 op_sel:[0,0,1]
	s_waitcnt lgkmcnt(2)
	v_mfma_scale_f32_32x32x64_f8f6f4 v[98:113], v[222:229], v[138:145], v[98:113], v194, v193 op_sel_hi:[0,0,0]
	ds_read_b128 v[222:225], v185 offset:34816
	ds_read_b128 v[226:229], v186 offset:34816
	v_exp_f32_e32 v0, v70
	v_exp_f32_e32 v177, v71
	v_exp_f32_e32 v179, v72
	v_exp_f32_e32 v254, v73
	v_add_f32_e32 v219, v0, v219
	v_add_f32_e32 v219, v177, v219
	v_cvt_pk_fp8_f32 v251, v0, v177
	v_add_f32_e32 v219, v179, v219
	v_add_f32_e32 v219, v254, v219
	v_cvt_pk_fp8_f32 v251, v179, v254 op_sel:[0,0,1]
	v_exp_f32_e32 v0, v74
	v_exp_f32_e32 v177, v75
	v_exp_f32_e32 v179, v76
	v_exp_f32_e32 v254, v77
	v_add_f32_e32 v219, v0, v219
	v_add_f32_e32 v219, v177, v219
	v_cvt_pk_fp8_f32 v252, v0, v177
	v_add_f32_e32 v219, v179, v219
	v_add_f32_e32 v219, v254, v219
	v_cvt_pk_fp8_f32 v252, v179, v254 op_sel:[0,0,1]
	s_waitcnt lgkmcnt(2)
	v_mfma_scale_f32_32x32x64_f8f6f4 v[114:129], v[90:97], v[130:137], v[114:129], v194, v193 op_sel_hi:[0,0,0]
	v_exp_f32_e32 v0, v78
	v_exp_f32_e32 v177, v79
	v_exp_f32_e32 v179, v80
	v_exp_f32_e32 v254, v81
	v_add_f32_e32 v219, v0, v219
	v_add_f32_e32 v219, v177, v219
	v_cvt_pk_fp8_f32 v253, v0, v177
	v_add_f32_e32 v219, v179, v219
	v_add_f32_e32 v219, v254, v219
	v_cvt_pk_fp8_f32 v253, v179, v254 op_sel:[0,0,1]
	ds_read_b128 v[90:93], v185 offset:43008
	ds_read_b128 v[94:97], v186 offset:43008
	ds_read_b128 v[82:85], v185 offset:45056
	ds_read_b128 v[86:89], v186 offset:45056
	ds_read_b128 v[74:77], v185 offset:47104
	ds_read_b128 v[78:81], v186 offset:47104
	ds_read_b128 v[66:69], v185 offset:49152
	ds_read_b128 v[70:73], v186 offset:49152
	s_waitcnt lgkmcnt(8)
	v_mfma_scale_f32_32x32x64_f8f6f4 v[98:113], v[222:229], v[130:137], v[98:113], v194, v193 op_sel_hi:[0,0,0]
	v_mov_b32_e32 v0, v219
	s_nop 1
	v_permlane32_swap_b32_e32 v219, v0
	v_add_f32_e32 v219, v219, v0
	v_fma_f32 v209, v209, v218, v219
	v_max_f32_e32 v177, v114, v115
	v_max3_f32 v177, v177, v116, v117
	v_max3_f32 v177, v177, v118, v119
	v_max3_f32 v177, v177, v120, v121
	v_max3_f32 v177, v177, v122, v123
	v_max3_f32 v177, v177, v124, v125
	v_max3_f32 v177, v177, v126, v127
	v_max3_f32 v177, v177, v128, v129
	s_waitcnt lgkmcnt(6)
	v_mfma_scale_f32_32x32x64_f8f6f4 v[50:65], v[246:253], v[90:97], v[50:65], v194, v194 op_sel_hi:[0,0,0]
	s_waitcnt vmcnt(0)
	ds_write_b128 v210, v[158:161] offset:8192
	ds_write_b128 v211, v[162:165] offset:24576
	s_waitcnt lgkmcnt(6)
	v_mfma_scale_f32_32x32x64_f8f6f4 v[34:49], v[246:253], v[82:89], v[34:49], v194, v194 op_sel_hi:[0,0,0]
	s_waitcnt lgkmcnt(0)
	s_barrier
	v_max_f32_e32 v0, v98, v99
	v_max3_f32 v0, v0, v100, v101
	v_max3_f32 v0, v0, v102, v103
	v_max3_f32 v0, v0, v104, v105
	s_waitcnt lgkmcnt(2)
	v_mfma_scale_f32_32x32x64_f8f6f4 v[18:33], v[246:253], v[74:81], v[18:33], v194, v194 op_sel_hi:[0,0,0]
	global_load_dwordx4 v[158:161], v176, s[18:19]
	global_load_dwordx4 v[162:165], v178, s[16:17]
	v_add_u32_e32 v176, 0x2000, v176
	v_add_u32_e32 v178, 0x20000, v178
	v_max3_f32 v0, v0, v106, v107
	v_max3_f32 v0, v0, v108, v109
	v_max3_f32 v0, v0, v110, v111
	v_max3_f32 v0, v0, v112, v113
	s_waitcnt lgkmcnt(0)
	v_mfma_scale_f32_32x32x64_f8f6f4 v[2:17], v[246:253], v[66:73], v[2:17], v194, v194 op_sel_hi:[0,0,0]
	v_max_f32_e32 v177, v177, v0
	v_mov_b32_e32 v0, v177
	v_mov_b32_e32 v221, 1.0
	s_nop 0
	v_permlane32_swap_b32_e32 v177, v0
	v_max_f32_e32 v177, v177, v0
	v_cmp_ge_f32_e32 vcc, s90, v177
	s_cmp_eq_u64 vcc, exec
	s_cbranch_scc0 .Lmla_s2_newmax
; __device__ __forceinline__ void finishSM9(f32x16& p0, f32x16& p1, float alpha, float& l_reg, v8i32& p8) {
; #pragma unroll
;   for (int r = 0; r < 16; ++r) { p0[r] = __builtin_amdgcn_exp2f(p0[r]); p1[r] = __builtin_amdgcn_exp2f(p1[r]); }
;   float ps = 0;
; #pragma unroll
;   for (int r = 0; r < 16; ++r) ps += p0[r];
; #pragma unroll
;   for (int r = 0; r < 16; ++r) ps += p1[r];
;   { auto rr = __builtin_amdgcn_permlane32_swap(__float_as_uint(ps), __float_as_uint(ps), false, false);
;     ps = __uint_as_float(rr[0]) + __uint_as_float(rr[1]); }
;   l_reg = l_reg * alpha + ps;
; #pragma unroll
;   for (int g = 0; g < 4; ++g) {
;     int w = __builtin_amdgcn_cvt_pk_fp8_f32(p0[4 * g], p0[4 * g + 1], 0, false); p8[g] = __builtin_amdgcn_cvt_pk_fp8_f32(p0[4 * g + 2], p0[4 * g + 3], w, true);
;     int u = __builtin_amdgcn_cvt_pk_fp8_f32(p1[4 * g], p1[4 * g + 1], 0, false); p8[4 + g] = __builtin_amdgcn_cvt_pk_fp8_f32(p1[4 * g + 2], p1[4 * g + 3], u, true); }
; }
; __device__ __forceinline__ void pv8(f32x16* o, const char* Vt, const v8i32 p8, int r32, int hi) {
;   const int sw = (r32 >> 2) & 3, a0 = r32 * 64 + (((hi * 2) ^ sw) << 4), a1 = r32 * 64 + (((hi * 2 + 1) ^ sw) << 4);
; #pragma unroll
;   for (int d0 = 0; d0 < 4; ++d0) {
;     const v8i32 vf = cat8(*reinterpret_cast<const v4i32*>(Vt + d0 * 2048 + a0), *reinterpret_cast<const v4i32*>(Vt + d0 * 2048 + a1));
;     o[d0] = __builtin_amdgcn_mfma_scale_f32_32x32x64_f8f6f4(p8, vf, o[d0], 0, 0, 0, 127, 0, 127); }
; }
; __device__ __forceinline__ void qkt9(f32x16& p0, f32x16& p1, const char* Kn, const char* Kr, const v8i32* qf, const float init, int r32, int hi) {
; #pragma unroll
;   for (int r = 0; r < 16; ++r) { p0[r] = init; p1[r] = init; }
; #pragma unroll
;   for (int s = 0; s < 2; ++s) { const int c0 = s * 4 + hi * 2;
;     const v8i32 a0 = cat8(*reinterpret_cast<const v4i32*>(Kn + KN8SW(r32, c0)), *reinterpret_cast<const v4i32*>(Kn + KN8SW(r32, c0 + 1)));
;     const v8i32 a1 = cat8(*reinterpret_cast<const v4i32*>(Kn + 4096 + KN8SW(r32, c0)), *reinterpret_cast<const v4i32*>(Kn + 4096 + KN8SW(r32, c0 + 1)));
;     p0 = __builtin_amdgcn_mfma_scale_f32_32x32x64_f8f6f4(a0, qf[s], p0, 0, 0, 0, 127, 0, 124);
;     p1 = __builtin_amdgcn_mfma_scale_f32_32x32x64_f8f6f4(a1, qf[s], p1, 0, 0, 0, 127, 0, 124); }
;   { const int c0 = hi * 2;
.Lmla_s2_cont:
	ds_read_b128 v[82:85], v215 offset:24576
	ds_read_b128 v[86:89], v216 offset:24576
	ds_read_b128 v[222:225], v215 offset:28672
	ds_read_b128 v[226:229], v216 offset:28672
	v_exp_f32_e32 v0, v114
	v_exp_f32_e32 v177, v115
	v_exp_f32_e32 v179, v116
	v_exp_f32_e32 v254, v117
	v_add_f32_e32 v219, v0, v177
	v_cvt_pk_fp8_f32 v246, v0, v177
	v_add_f32_e32 v219, v179, v219
	v_add_f32_e32 v219, v254, v219
	v_cvt_pk_fp8_f32 v246, v179, v254 op_sel:[0,0,1]
	s_waitcnt lgkmcnt(2)
	v_mfma_scale_f32_32x32x64_f8f6f4 v[82:97], v[82:89], v[146:153], v[230:245], v194, v193 op_sel_hi:[0,0,0]
	v_exp_f32_e32 v0, v118
	v_exp_f32_e32 v177, v119
	v_exp_f32_e32 v179, v120
	v_exp_f32_e32 v254, v121
	v_add_f32_e32 v219, v0, v219
	v_add_f32_e32 v219, v177, v219
	v_cvt_pk_fp8_f32 v247, v0, v177
	v_add_f32_e32 v219, v179, v219
	v_add_f32_e32 v219, v254, v219
	v_cvt_pk_fp8_f32 v247, v179, v254 op_sel:[0,0,1]
	ds_read_b128 v[114:117], v213 offset:24576
	ds_read_b128 v[118:121], v214 offset:24576
	s_waitcnt lgkmcnt(2)
	v_mfma_scale_f32_32x32x64_f8f6f4 v[66:81], v[222:229], v[146:153], v[230:245], v194, v193 op_sel_hi:[0,0,0]
	ds_read_b128 v[222:225], v213 offset:28672
	ds_read_b128 v[226:229], v214 offset:28672
	v_exp_f32_e32 v0, v122
	v_exp_f32_e32 v177, v123
	v_exp_f32_e32 v179, v124
	v_exp_f32_e32 v254, v125
	v_add_f32_e32 v219, v0, v219
	v_add_f32_e32 v219, v177, v219
	v_cvt_pk_fp8_f32 v248, v0, v177
	v_add_f32_e32 v219, v179, v219
	v_add_f32_e32 v219, v254, v219
	v_cvt_pk_fp8_f32 v248, v179, v254 op_sel:[0,0,1]
	v_exp_f32_e32 v0, v126
	v_exp_f32_e32 v177, v127
	v_exp_f32_e32 v179, v128
	v_exp_f32_e32 v254, v129
	v_add_f32_e32 v219, v0, v219
	v_add_f32_e32 v219, v177, v219
	v_cvt_pk_fp8_f32 v249, v0, v177
	v_add_f32_e32 v219, v179, v219
	v_add_f32_e32 v219, v254, v219
	v_cvt_pk_fp8_f32 v249, v179, v254 op_sel:[0,0,1]
	ds_read_b128 v[122:125], v185 offset:36864
	ds_read_b128 v[126:129], v186 offset:36864
	s_waitcnt lgkmcnt(4)
	v_mfma_scale_f32_32x32x64_f8f6f4 v[82:97], v[114:121], v[138:145], v[82:97], v194, v193 op_sel_hi:[0,0,0]
	v_exp_f32_e32 v0, v98
	v_exp_f32_e32 v177, v99
	v_exp_f32_e32 v179, v100
	v_exp_f32_e32 v254, v101
	v_add_f32_e32 v219, v0, v219
	v_add_f32_e32 v219, v177, v219
	v_cvt_pk_fp8_f32 v250, v0, v177
	v_add_f32_e32 v219, v179, v219
	v_add_f32_e32 v219, v254, v219
	v_cvt_pk_fp8_f32 v250, v179, v254 op_sel:[0,0,1]
	s_waitcnt lgkmcnt(2)
	v_mfma_scale_f32_32x32x64_f8f6f4 v[66:81], v[222:229], v[138:145], v[66:81], v194, v193 op_sel_hi:[0,0,0]
	ds_read_b128 v[222:225], v185 offset:38912
	ds_read_b128 v[226:229], v186 offset:38912
	v_exp_f32_e32 v0, v102
	v_exp_f32_e32 v177, v103
	v_exp_f32_e32 v179, v104
	v_exp_f32_e32 v254, v105
	v_add_f32_e32 v219, v0, v219
	v_add_f32_e32 v219, v177, v219
	v_cvt_pk_fp8_f32 v251, v0, v177
	v_add_f32_e32 v219, v179, v219
	v_add_f32_e32 v219, v254, v219
	v_cvt_pk_fp8_f32 v251, v179, v254 op_sel:[0,0,1]
	v_exp_f32_e32 v0, v106
	v_exp_f32_e32 v177, v107
	v_exp_f32_e32 v179, v108
	v_exp_f32_e32 v254, v109
	v_add_f32_e32 v219, v0, v219
	v_add_f32_e32 v219, v177, v219
	v_cvt_pk_fp8_f32 v252, v0, v177
	v_add_f32_e32 v219, v179, v219
	v_add_f32_e32 v219, v254, v219
	v_cvt_pk_fp8_f32 v252, v179, v254 op_sel:[0,0,1]
	s_waitcnt lgkmcnt(2)
	v_mfma_scale_f32_32x32x64_f8f6f4 v[82:97], v[122:129], v[130:137], v[82:97], v194, v193 op_sel_hi:[0,0,0]
	v_exp_f32_e32 v0, v110
	v_exp_f32_e32 v177, v111
	v_exp_f32_e32 v179, v112
	v_exp_f32_e32 v254, v113
	v_add_f32_e32 v219, v0, v219
	v_add_f32_e32 v219, v177, v219
	v_cvt_pk_fp8_f32 v253, v0, v177
	v_add_f32_e32 v219, v179, v219
	v_add_f32_e32 v219, v254, v219
	v_cvt_pk_fp8_f32 v253, v179, v254 op_sel:[0,0,1]
	ds_read_b128 v[122:125], v185 offset:0
	ds_read_b128 v[126:129], v186 offset:0
	ds_read_b128 v[114:117], v185 offset:2048
	ds_read_b128 v[118:121], v186 offset:2048
	ds_read_b128 v[106:109], v185 offset:4096
	ds_read_b128 v[110:113], v186 offset:4096
	ds_read_b128 v[98:101], v185 offset:6144
	ds_read_b128 v[102:105], v186 offset:6144
	s_waitcnt lgkmcnt(8)
	v_mfma_scale_f32_32x32x64_f8f6f4 v[66:81], v[222:229], v[130:137], v[66:81], v194, v193 op_sel_hi:[0,0,0]
	v_mov_b32_e32 v0, v219
	s_nop 1
	v_permlane32_swap_b32_e32 v219, v0
	v_add_f32_e32 v219, v219, v0
	v_fma_f32 v209, v209, v221, v219
	v_max_f32_e32 v177, v82, v83
	v_max3_f32 v177, v177, v84, v85
	v_max3_f32 v177, v177, v86, v87
	v_max3_f32 v177, v177, v88, v89
	v_max3_f32 v177, v177, v90, v91
	v_max3_f32 v177, v177, v92, v93
	v_max3_f32 v177, v177, v94, v95
	v_max3_f32 v177, v177, v96, v97
	s_waitcnt lgkmcnt(6)
	v_mfma_scale_f32_32x32x64_f8f6f4 v[50:65], v[246:253], v[122:129], v[50:65], v194, v194 op_sel_hi:[0,0,0]
	s_waitcnt vmcnt(0)
	ds_write_b128 v210, v[158:161] offset:43008
	ds_write_b128 v211, v[162:165] offset:51200
	s_waitcnt lgkmcnt(6)
	v_mfma_scale_f32_32x32x64_f8f6f4 v[34:49], v[246:253], v[114:121], v[34:49], v194, v194 op_sel_hi:[0,0,0]
	s_waitcnt lgkmcnt(0)
	s_barrier
	v_max_f32_e32 v0, v66, v67
	v_max3_f32 v0, v0, v68, v69
	v_max3_f32 v0, v0, v70, v71
	v_max3_f32 v0, v0, v72, v73
	s_waitcnt lgkmcnt(2)
	v_mfma_scale_f32_32x32x64_f8f6f4 v[18:33], v[246:253], v[106:113], v[18:33], v194, v194 op_sel_hi:[0,0,0]
	global_load_dwordx4 v[158:161], v176, s[18:19]
	global_load_dwordx4 v[162:165], v178, s[16:17]
	v_add_u32_e32 v176, 0x2000, v176
	v_add_u32_e32 v178, 0x20000, v178
	v_max3_f32 v0, v0, v74, v75
	v_max3_f32 v0, v0, v76, v77
	v_max3_f32 v0, v0, v78, v79
	v_max3_f32 v0, v0, v80, v81
	s_waitcnt lgkmcnt(0)
	v_mfma_scale_f32_32x32x64_f8f6f4 v[2:17], v[246:253], v[98:105], v[2:17], v194, v194 op_sel_hi:[0,0,0]
	v_max_f32_e32 v177, v177, v0
	v_mov_b32_e32 v0, v177
	v_mov_b32_e32 v218, 1.0
	s_nop 0
	v_permlane32_swap_b32_e32 v177, v0
	v_max_f32_e32 v177, v177, v0
	v_cmp_ge_f32_e32 vcc, s90, v177
	s_cmp_eq_u64 vcc, exec
	s_cbranch_scc0 .Lmla_s3_newmax
; __device__ __forceinline__ void finishSM9(f32x16& p0, f32x16& p1, float alpha, float& l_reg, v8i32& p8) {
; #pragma unroll
;   for (int r = 0; r < 16; ++r) { p0[r] = __builtin_amdgcn_exp2f(p0[r]); p1[r] = __builtin_amdgcn_exp2f(p1[r]); }
;   float ps = 0;
; #pragma unroll
;   for (int r = 0; r < 16; ++r) ps += p0[r];
; #pragma unroll
;   for (int r = 0; r < 16; ++r) ps += p1[r];
;   { auto rr = __builtin_amdgcn_permlane32_swap(__float_as_uint(ps), __float_as_uint(ps), false, false);
;     ps = __uint_as_float(rr[0]) + __uint_as_float(rr[1]); }
;   l_reg = l_reg * alpha + ps;
; #pragma unroll
;   for (int g = 0; g < 4; ++g) {
;     int w = __builtin_amdgcn_cvt_pk_fp8_f32(p0[4 * g], p0[4 * g + 1], 0, false); p8[g] = __builtin_amdgcn_cvt_pk_fp8_f32(p0[4 * g + 2], p0[4 * g + 3], w, true);
;     int u = __builtin_amdgcn_cvt_pk_fp8_f32(p1[4 * g], p1[4 * g + 1], 0, false); p8[4 + g] = __builtin_amdgcn_cvt_pk_fp8_f32(p1[4 * g + 2], p1[4 * g + 3], u, true); }
; }
; __device__ __forceinline__ void pv8(f32x16* o, const char* Vt, const v8i32 p8, int r32, int hi) {
;   const int sw = (r32 >> 2) & 3, a0 = r32 * 64 + (((hi * 2) ^ sw) << 4), a1 = r32 * 64 + (((hi * 2 + 1) ^ sw) << 4);
; #pragma unroll
;   for (int d0 = 0; d0 < 4; ++d0) {
;     const v8i32 vf = cat8(*reinterpret_cast<const v4i32*>(Vt + d0 * 2048 + a0), *reinterpret_cast<const v4i32*>(Vt + d0 * 2048 + a1));
;     o[d0] = __builtin_amdgcn_mfma_scale_f32_32x32x64_f8f6f4(p8, vf, o[d0], 0, 0, 0, 127, 0, 127); }
; }
; __device__ __forceinline__ void qkt9(f32x16& p0, f32x16& p1, const char* Kn, const char* Kr, const v8i32* qf, const float init, int r32, int hi) {
; #pragma unroll
;   for (int r = 0; r < 16; ++r) { p0[r] = init; p1[r] = init; }
; #pragma unroll
;   for (int s = 0; s < 2; ++s) { const int c0 = s * 4 + hi * 2;
;     const v8i32 a0 = cat8(*reinterpret_cast<const v4i32*>(Kn + KN8SW(r32, c0)), *reinterpret_cast<const v4i32*>(Kn + KN8SW(r32, c0 + 1)));
;     const v8i32 a1 = cat8(*reinterpret_cast<const v4i32*>(Kn + 4096 + KN8SW(r32, c0)), *reinterpret_cast<const v4i32*>(Kn + 4096 + KN8SW(r32, c0 + 1)));
;     p0 = __builtin_amdgcn_mfma_scale_f32_32x32x64_f8f6f4(a0, qf[s], p0, 0, 0, 0, 127, 0, 124);
;     p1 = __builtin_amdgcn_mfma_scale_f32_32x32x64_f8f6f4(a1, qf[s], p1, 0, 0, 0, 127, 0, 124); }
;   { const int c0 = hi * 2;
.Lmla_s3_cont:
	ds_read_b128 v[114:117], v215 offset:51200
	ds_read_b128 v[118:121], v216 offset:51200
	ds_read_b128 v[222:225], v215 offset:55296
	ds_read_b128 v[226:229], v216 offset:55296
	v_exp_f32_e32 v0, v82
	v_exp_f32_e32 v177, v83
	v_exp_f32_e32 v179, v84
	v_exp_f32_e32 v254, v85
	v_add_f32_e32 v219, v0, v177
	v_cvt_pk_fp8_f32 v246, v0, v177
	v_add_f32_e32 v219, v179, v219
	v_add_f32_e32 v219, v254, v219
	v_cvt_pk_fp8_f32 v246, v179, v254 op_sel:[0,0,1]
	s_waitcnt lgkmcnt(2)
	v_mfma_scale_f32_32x32x64_f8f6f4 v[114:129], v[114:121], v[146:153], v[230:245], v194, v193 op_sel_hi:[0,0,0]
	v_exp_f32_e32 v0, v86
	v_exp_f32_e32 v177, v87
	v_exp_f32_e32 v179, v88
	v_exp_f32_e32 v254, v89
	v_add_f32_e32 v219, v0, v219
	v_add_f32_e32 v219, v177, v219
	v_cvt_pk_fp8_f32 v247, v0, v177
	v_add_f32_e32 v219, v179, v219
	v_add_f32_e32 v219, v254, v219
	v_cvt_pk_fp8_f32 v247, v179, v254 op_sel:[0,0,1]
	ds_read_b128 v[82:85], v213 offset:51200
	ds_read_b128 v[86:89], v214 offset:51200
	s_waitcnt lgkmcnt(2)
	v_mfma_scale_f32_32x32x64_f8f6f4 v[98:113], v[222:229], v[146:153], v[230:245], v194, v193 op_sel_hi:[0,0,0]
	ds_read_b128 v[222:225], v213 offset:55296
	ds_read_b128 v[226:229], v214 offset:55296
	v_exp_f32_e32 v0, v90
	v_exp_f32_e32 v177, v91
	v_exp_f32_e32 v179, v92
	v_exp_f32_e32 v254, v93
	v_add_f32_e32 v219, v0, v219
	v_add_f32_e32 v219, v177, v219
	v_cvt_pk_fp8_f32 v248, v0, v177
	v_add_f32_e32 v219, v179, v219
	v_add_f32_e32 v219, v254, v219
	v_cvt_pk_fp8_f32 v248, v179, v254 op_sel:[0,0,1]
	v_exp_f32_e32 v0, v94
	v_exp_f32_e32 v177, v95
	v_exp_f32_e32 v179, v96
	v_exp_f32_e32 v254, v97
	v_add_f32_e32 v219, v0, v219
	v_add_f32_e32 v219, v177, v219
	v_cvt_pk_fp8_f32 v249, v0, v177
	v_add_f32_e32 v219, v179, v219
	v_add_f32_e32 v219, v254, v219
	v_cvt_pk_fp8_f32 v249, v179, v254 op_sel:[0,0,1]
	ds_read_b128 v[90:93], v185 offset:59392
	ds_read_b128 v[94:97], v186 offset:59392
	s_waitcnt lgkmcnt(4)
	v_mfma_scale_f32_32x32x64_f8f6f4 v[114:129], v[82:89], v[138:145], v[114:129], v194, v193 op_sel_hi:[0,0,0]
	v_exp_f32_e32 v0, v66
	v_exp_f32_e32 v177, v67
	v_exp_f32_e32 v179, v68
	v_exp_f32_e32 v254, v69
	v_add_f32_e32 v219, v0, v219
	v_add_f32_e32 v219, v177, v219
	v_cvt_pk_fp8_f32 v250, v0, v177
	v_add_f32_e32 v219, v179, v219
	v_add_f32_e32 v219, v254, v219
	v_cvt_pk_fp8_f32 v250, v179, v254 op_sel:[0,0,1]
	s_waitcnt lgkmcnt(2)
	v_mfma_scale_f32_32x32x64_f8f6f4 v[98:113], v[222:229], v[138:145], v[98:113], v194, v193 op_sel_hi:[0,0,0]
	ds_read_b128 v[222:225], v185 offset:61440
	ds_read_b128 v[226:229], v186 offset:61440
	v_exp_f32_e32 v0, v70
	v_exp_f32_e32 v177, v71
	v_exp_f32_e32 v179, v72
	v_exp_f32_e32 v254, v73
	v_add_f32_e32 v219, v0, v219
	v_add_f32_e32 v219, v177, v219
	v_cvt_pk_fp8_f32 v251, v0, v177
	v_add_f32_e32 v219, v179, v219
	v_add_f32_e32 v219, v254, v219
	v_cvt_pk_fp8_f32 v251, v179, v254 op_sel:[0,0,1]
	v_exp_f32_e32 v0, v74
	v_exp_f32_e32 v177, v75
	v_exp_f32_e32 v179, v76
	v_exp_f32_e32 v254, v77
	v_add_f32_e32 v219, v0, v219
	v_add_f32_e32 v219, v177, v219
	v_cvt_pk_fp8_f32 v252, v0, v177
	v_add_f32_e32 v219, v179, v219
	v_add_f32_e32 v219, v254, v219
	v_cvt_pk_fp8_f32 v252, v179, v254 op_sel:[0,0,1]
	s_waitcnt lgkmcnt(2)
	v_mfma_scale_f32_32x32x64_f8f6f4 v[114:129], v[90:97], v[130:137], v[114:129], v194, v193 op_sel_hi:[0,0,0]
	v_exp_f32_e32 v0, v78
	v_exp_f32_e32 v177, v79
	v_exp_f32_e32 v179, v80
	v_exp_f32_e32 v254, v81
	v_add_f32_e32 v219, v0, v219
	v_add_f32_e32 v219, v177, v219
	v_cvt_pk_fp8_f32 v253, v0, v177
	v_add_f32_e32 v219, v179, v219
	v_add_f32_e32 v219, v254, v219
	v_cvt_pk_fp8_f32 v253, v179, v254 op_sel:[0,0,1]
	ds_read_b128 v[90:93], v185 offset:8192
	ds_read_b128 v[94:97], v186 offset:8192
	ds_read_b128 v[82:85], v185 offset:10240
	ds_read_b128 v[86:89], v186 offset:10240
	ds_read_b128 v[74:77], v185 offset:12288
	ds_read_b128 v[78:81], v186 offset:12288
	ds_read_b128 v[66:69], v185 offset:14336
	ds_read_b128 v[70:73], v186 offset:14336
	s_waitcnt lgkmcnt(8)
	v_mfma_scale_f32_32x32x64_f8f6f4 v[98:113], v[222:229], v[130:137], v[98:113], v194, v193 op_sel_hi:[0,0,0]
	v_mov_b32_e32 v0, v219
	s_nop 1
	v_permlane32_swap_b32_e32 v219, v0
	v_add_f32_e32 v219, v219, v0
	v_fma_f32 v209, v209, v218, v219
	v_max_f32_e32 v177, v114, v115
	v_max3_f32 v177, v177, v116, v117
	v_max3_f32 v177, v177, v118, v119
	v_max3_f32 v177, v177, v120, v121
	v_max3_f32 v177, v177, v122, v123
	v_max3_f32 v177, v177, v124, v125
	v_max3_f32 v177, v177, v126, v127
	v_max3_f32 v177, v177, v128, v129
	s_waitcnt lgkmcnt(6)
	v_mfma_scale_f32_32x32x64_f8f6f4 v[50:65], v[246:253], v[90:97], v[50:65], v194, v194 op_sel_hi:[0,0,0]
	s_waitcnt vmcnt(0)
	ds_write_b128 v210, v[158:161]
	ds_write_b128 v211, v[162:165] offset:16384
	s_waitcnt lgkmcnt(6)
	v_mfma_scale_f32_32x32x64_f8f6f4 v[34:49], v[246:253], v[82:89], v[34:49], v194, v194 op_sel_hi:[0,0,0]
	s_waitcnt lgkmcnt(0)
	s_barrier
	v_max_f32_e32 v0, v98, v99
	v_max3_f32 v0, v0, v100, v101
	v_max3_f32 v0, v0, v102, v103
	v_max3_f32 v0, v0, v104, v105
	s_waitcnt lgkmcnt(2)
	v_mfma_scale_f32_32x32x64_f8f6f4 v[18:33], v[246:253], v[74:81], v[18:33], v194, v194 op_sel_hi:[0,0,0]
	global_load_dwordx4 v[158:161], v176, s[18:19]
	global_load_dwordx4 v[162:165], v178, s[16:17]
	v_add_u32_e32 v176, 0x2000, v176
	v_add_u32_e32 v178, 0x20000, v178
	v_max3_f32 v0, v0, v106, v107
	v_max3_f32 v0, v0, v108, v109
	v_max3_f32 v0, v0, v110, v111
	v_max3_f32 v0, v0, v112, v113
	s_waitcnt lgkmcnt(0)
	v_mfma_scale_f32_32x32x64_f8f6f4 v[2:17], v[246:253], v[66:73], v[2:17], v194, v194 op_sel_hi:[0,0,0]
	v_max_f32_e32 v177, v177, v0
	v_mov_b32_e32 v0, v177
	v_mov_b32_e32 v221, 1.0
	s_nop 0
	v_permlane32_swap_b32_e32 v177, v0
	v_max_f32_e32 v177, v177, v0
	v_cmp_ge_f32_e32 vcc, s90, v177
	s_cmp_eq_u64 vcc, exec
	s_cbranch_scc0 .Lmla_s4_newmax
; __device__ __forceinline__ void finishSM9(f32x16& p0, f32x16& p1, float alpha, float& l_reg, v8i32& p8) {
; #pragma unroll
;   for (int r = 0; r < 16; ++r) { p0[r] = __builtin_amdgcn_exp2f(p0[r]); p1[r] = __builtin_amdgcn_exp2f(p1[r]); }
;   float ps = 0;
; #pragma unroll
;   for (int r = 0; r < 16; ++r) ps += p0[r];
; #pragma unroll
;   for (int r = 0; r < 16; ++r) ps += p1[r];
;   { auto rr = __builtin_amdgcn_permlane32_swap(__float_as_uint(ps), __float_as_uint(ps), false, false);
;     ps = __uint_as_float(rr[0]) + __uint_as_float(rr[1]); }
;   l_reg = l_reg * alpha + ps;
; #pragma unroll
;   for (int g = 0; g < 4; ++g) {
;     int w = __builtin_amdgcn_cvt_pk_fp8_f32(p0[4 * g], p0[4 * g + 1], 0, false); p8[g] = __builtin_amdgcn_cvt_pk_fp8_f32(p0[4 * g + 2], p0[4 * g + 3], w, true);
;     int u = __builtin_amdgcn_cvt_pk_fp8_f32(p1[4 * g], p1[4 * g + 1], 0, false); p8[4 + g] = __builtin_amdgcn_cvt_pk_fp8_f32(p1[4 * g + 2], p1[4 * g + 3], u, true); }
; }
; __device__ __forceinline__ void pv8(f32x16* o, const char* Vt, const v8i32 p8, int r32, int hi) {
;   const int sw = (r32 >> 2) & 3, a0 = r32 * 64 + (((hi * 2) ^ sw) << 4), a1 = r32 * 64 + (((hi * 2 + 1) ^ sw) << 4);
; #pragma unroll
;   for (int d0 = 0; d0 < 4; ++d0) {
;     const v8i32 vf = cat8(*reinterpret_cast<const v4i32*>(Vt + d0 * 2048 + a0), *reinterpret_cast<const v4i32*>(Vt + d0 * 2048 + a1));
;     o[d0] = __builtin_amdgcn_mfma_scale_f32_32x32x64_f8f6f4(p8, vf, o[d0], 0, 0, 0, 127, 0, 127); }
; }
; __device__ __forceinline__ void qkt9(f32x16& p0, f32x16& p1, const char* Kn, const char* Kr, const v8i32* qf, const float init, int r32, int hi) {
; #pragma unroll
;   for (int r = 0; r < 16; ++r) { p0[r] = init; p1[r] = init; }
; #pragma unroll
;   for (int s = 0; s < 2; ++s) { const int c0 = s * 4 + hi * 2;
;     const v8i32 a0 = cat8(*reinterpret_cast<const v4i32*>(Kn + KN8SW(r32, c0)), *reinterpret_cast<const v4i32*>(Kn + KN8SW(r32, c0 + 1)));
;     const v8i32 a1 = cat8(*reinterpret_cast<const v4i32*>(Kn + 4096 + KN8SW(r32, c0)), *reinterpret_cast<const v4i32*>(Kn + 4096 + KN8SW(r32, c0 + 1)));
;     p0 = __builtin_amdgcn_mfma_scale_f32_32x32x64_f8f6f4(a0, qf[s], p0, 0, 0, 0, 127, 0, 124);
;     p1 = __builtin_amdgcn_mfma_scale_f32_32x32x64_f8f6f4(a1, qf[s], p1, 0, 0, 0, 127, 0, 124); }
;   { const int c0 = hi * 2;
.Lmla_s4_cont:
	ds_read_b128 v[82:85], v215 offset:16384
	ds_read_b128 v[86:89], v216 offset:16384
	ds_read_b128 v[222:225], v215 offset:20480
	ds_read_b128 v[226:229], v216 offset:20480
	v_exp_f32_e32 v0, v114
	v_exp_f32_e32 v177, v115
	v_exp_f32_e32 v179, v116
	v_exp_f32_e32 v254, v117
	v_add_f32_e32 v219, v0, v177
	v_cvt_pk_fp8_f32 v246, v0, v177
	v_add_f32_e32 v219, v179, v219
	v_add_f32_e32 v219, v254, v219
	v_cvt_pk_fp8_f32 v246, v179, v254 op_sel:[0,0,1]
	s_waitcnt lgkmcnt(2)
	v_mfma_scale_f32_32x32x64_f8f6f4 v[82:97], v[82:89], v[146:153], v[230:245], v194, v193 op_sel_hi:[0,0,0]
	v_exp_f32_e32 v0, v118
	v_exp_f32_e32 v177, v119
	v_exp_f32_e32 v179, v120
	v_exp_f32_e32 v254, v121
	v_add_f32_e32 v219, v0, v219
	v_add_f32_e32 v219, v177, v219
	v_cvt_pk_fp8_f32 v247, v0, v177
	v_add_f32_e32 v219, v179, v219
	v_add_f32_e32 v219, v254, v219
	v_cvt_pk_fp8_f32 v247, v179, v254 op_sel:[0,0,1]
	ds_read_b128 v[114:117], v213 offset:16384
	ds_read_b128 v[118:121], v214 offset:16384
	s_waitcnt lgkmcnt(2)
	v_mfma_scale_f32_32x32x64_f8f6f4 v[66:81], v[222:229], v[146:153], v[230:245], v194, v193 op_sel_hi:[0,0,0]
	ds_read_b128 v[222:225], v213 offset:20480
	ds_read_b128 v[226:229], v214 offset:20480
	v_exp_f32_e32 v0, v122
	v_exp_f32_e32 v177, v123
	v_exp_f32_e32 v179, v124
	v_exp_f32_e32 v254, v125
	v_add_f32_e32 v219, v0, v219
	v_add_f32_e32 v219, v177, v219
	v_cvt_pk_fp8_f32 v248, v0, v177
	v_add_f32_e32 v219, v179, v219
	v_add_f32_e32 v219, v254, v219
	v_cvt_pk_fp8_f32 v248, v179, v254 op_sel:[0,0,1]
	v_exp_f32_e32 v0, v126
	v_exp_f32_e32 v177, v127
	v_exp_f32_e32 v179, v128
	v_exp_f32_e32 v254, v129
	v_add_f32_e32 v219, v0, v219
	v_add_f32_e32 v219, v177, v219
	v_cvt_pk_fp8_f32 v249, v0, v177
	v_add_f32_e32 v219, v179, v219
	v_add_f32_e32 v219, v254, v219
	v_cvt_pk_fp8_f32 v249, v179, v254 op_sel:[0,0,1]
	ds_read_b128 v[122:125], v185 offset:32768
	ds_read_b128 v[126:129], v186 offset:32768
	s_waitcnt lgkmcnt(4)
	v_mfma_scale_f32_32x32x64_f8f6f4 v[82:97], v[114:121], v[138:145], v[82:97], v194, v193 op_sel_hi:[0,0,0]
	v_exp_f32_e32 v0, v98
	v_exp_f32_e32 v177, v99
	v_exp_f32_e32 v179, v100
	v_exp_f32_e32 v254, v101
	v_add_f32_e32 v219, v0, v219
	v_add_f32_e32 v219, v177, v219
	v_cvt_pk_fp8_f32 v250, v0, v177
	v_add_f32_e32 v219, v179, v219
	v_add_f32_e32 v219, v254, v219
	v_cvt_pk_fp8_f32 v250, v179, v254 op_sel:[0,0,1]
	s_waitcnt lgkmcnt(2)
	v_mfma_scale_f32_32x32x64_f8f6f4 v[66:81], v[222:229], v[138:145], v[66:81], v194, v193 op_sel_hi:[0,0,0]
	ds_read_b128 v[222:225], v185 offset:34816
	ds_read_b128 v[226:229], v186 offset:34816
	v_exp_f32_e32 v0, v102
	v_exp_f32_e32 v177, v103
	v_exp_f32_e32 v179, v104
	v_exp_f32_e32 v254, v105
	v_add_f32_e32 v219, v0, v219
	v_add_f32_e32 v219, v177, v219
	v_cvt_pk_fp8_f32 v251, v0, v177
	v_add_f32_e32 v219, v179, v219
	v_add_f32_e32 v219, v254, v219
	v_cvt_pk_fp8_f32 v251, v179, v254 op_sel:[0,0,1]
	v_exp_f32_e32 v0, v106
	v_exp_f32_e32 v177, v107
	v_exp_f32_e32 v179, v108
	v_exp_f32_e32 v254, v109
	v_add_f32_e32 v219, v0, v219
	v_add_f32_e32 v219, v177, v219
	v_cvt_pk_fp8_f32 v252, v0, v177
	v_add_f32_e32 v219, v179, v219
	v_add_f32_e32 v219, v254, v219
	v_cvt_pk_fp8_f32 v252, v179, v254 op_sel:[0,0,1]
	s_waitcnt lgkmcnt(2)
	v_mfma_scale_f32_32x32x64_f8f6f4 v[82:97], v[122:129], v[130:137], v[82:97], v194, v193 op_sel_hi:[0,0,0]
	v_exp_f32_e32 v0, v110
	v_exp_f32_e32 v177, v111
	v_exp_f32_e32 v179, v112
	v_exp_f32_e32 v254, v113
	v_add_f32_e32 v219, v0, v219
	v_add_f32_e32 v219, v177, v219
	v_cvt_pk_fp8_f32 v253, v0, v177
	v_add_f32_e32 v219, v179, v219
	v_add_f32_e32 v219, v254, v219
	v_cvt_pk_fp8_f32 v253, v179, v254 op_sel:[0,0,1]
	ds_read_b128 v[122:125], v185 offset:43008
	ds_read_b128 v[126:129], v186 offset:43008
	ds_read_b128 v[114:117], v185 offset:45056
	ds_read_b128 v[118:121], v186 offset:45056
	ds_read_b128 v[106:109], v185 offset:47104
	ds_read_b128 v[110:113], v186 offset:47104
	ds_read_b128 v[98:101], v185 offset:49152
	ds_read_b128 v[102:105], v186 offset:49152
	s_waitcnt lgkmcnt(8)
	v_mfma_scale_f32_32x32x64_f8f6f4 v[66:81], v[222:229], v[130:137], v[66:81], v194, v193 op_sel_hi:[0,0,0]
	v_mov_b32_e32 v0, v219
	s_nop 1
	v_permlane32_swap_b32_e32 v219, v0
	v_add_f32_e32 v219, v219, v0
	v_fma_f32 v209, v209, v221, v219
	v_max_f32_e32 v177, v82, v83
	v_max3_f32 v177, v177, v84, v85
	v_max3_f32 v177, v177, v86, v87
	v_max3_f32 v177, v177, v88, v89
	v_max3_f32 v177, v177, v90, v91
	v_max3_f32 v177, v177, v92, v93
	v_max3_f32 v177, v177, v94, v95
	v_max3_f32 v177, v177, v96, v97
	s_waitcnt lgkmcnt(6)
	v_mfma_scale_f32_32x32x64_f8f6f4 v[50:65], v[246:253], v[122:129], v[50:65], v194, v194 op_sel_hi:[0,0,0]
	s_waitcnt vmcnt(0)
	ds_write_b128 v210, v[158:161] offset:8192
	ds_write_b128 v211, v[162:165] offset:24576
	s_waitcnt lgkmcnt(6)
	v_mfma_scale_f32_32x32x64_f8f6f4 v[34:49], v[246:253], v[114:121], v[34:49], v194, v194 op_sel_hi:[0,0,0]
	s_waitcnt lgkmcnt(0)
	s_barrier
	v_max_f32_e32 v0, v66, v67
	v_max3_f32 v0, v0, v68, v69
	v_max3_f32 v0, v0, v70, v71
	v_max3_f32 v0, v0, v72, v73
	s_waitcnt lgkmcnt(2)
	v_mfma_scale_f32_32x32x64_f8f6f4 v[18:33], v[246:253], v[106:113], v[18:33], v194, v194 op_sel_hi:[0,0,0]
	global_load_dwordx4 v[158:161], v176, s[18:19]
	global_load_dwordx4 v[162:165], v178, s[16:17]
	v_add_u32_e32 v176, 0x2000, v176
	v_add_u32_e32 v178, 0x20000, v178
	v_max3_f32 v0, v0, v74, v75
	v_max3_f32 v0, v0, v76, v77
	v_max3_f32 v0, v0, v78, v79
	v_max3_f32 v0, v0, v80, v81
	s_waitcnt lgkmcnt(0)
	v_mfma_scale_f32_32x32x64_f8f6f4 v[2:17], v[246:253], v[98:105], v[2:17], v194, v194 op_sel_hi:[0,0,0]
	v_max_f32_e32 v177, v177, v0
	v_mov_b32_e32 v0, v177
	v_mov_b32_e32 v218, 1.0
	s_nop 0
	v_permlane32_swap_b32_e32 v177, v0
	v_max_f32_e32 v177, v177, v0
	v_cmp_ge_f32_e32 vcc, s90, v177
	s_cmp_eq_u64 vcc, exec
	s_cbranch_scc0 .Lmla_s5_newmax
; __device__ __forceinline__ void finishSM9(f32x16& p0, f32x16& p1, float alpha, float& l_reg, v8i32& p8) {
; #pragma unroll
;   for (int r = 0; r < 16; ++r) { p0[r] = __builtin_amdgcn_exp2f(p0[r]); p1[r] = __builtin_amdgcn_exp2f(p1[r]); }
;   float ps = 0;
; #pragma unroll
;   for (int r = 0; r < 16; ++r) ps += p0[r];
; #pragma unroll
;   for (int r = 0; r < 16; ++r) ps += p1[r];
;   { auto rr = __builtin_amdgcn_permlane32_swap(__float_as_uint(ps), __float_as_uint(ps), false, false);
;     ps = __uint_as_float(rr[0]) + __uint_as_float(rr[1]); }
;   l_reg = l_reg * alpha + ps;
; #pragma unroll
;   for (int g = 0; g < 4; ++g) {
;     int w = __builtin_amdgcn_cvt_pk_fp8_f32(p0[4 * g], p0[4 * g + 1], 0, false); p8[g] = __builtin_amdgcn_cvt_pk_fp8_f32(p0[4 * g + 2], p0[4 * g + 3], w, true);
;     int u = __builtin_amdgcn_cvt_pk_fp8_f32(p1[4 * g], p1[4 * g + 1], 0, false); p8[4 + g] = __builtin_amdgcn_cvt_pk_fp8_f32(p1[4 * g + 2], p1[4 * g + 3], u, true); }
; }
; __device__ __forceinline__ void pv8(f32x16* o, const char* Vt, const v8i32 p8, int r32, int hi) {
;   const int sw = (r32 >> 2) & 3, a0 = r32 * 64 + (((hi * 2) ^ sw) << 4), a1 = r32 * 64 + (((hi * 2 + 1) ^ sw) << 4);
; #pragma unroll
;   for (int d0 = 0; d0 < 4; ++d0) {
;     const v8i32 vf = cat8(*reinterpret_cast<const v4i32*>(Vt + d0 * 2048 + a0), *reinterpret_cast<const v4i32*>(Vt + d0 * 2048 + a1));
;     o[d0] = __builtin_amdgcn_mfma_scale_f32_32x32x64_f8f6f4(p8, vf, o[d0], 0, 0, 0, 127, 0, 127); }
; }
; __device__ __forceinline__ void qkt9(f32x16& p0, f32x16& p1, const char* Kn, const char* Kr, const v8i32* qf, const float init, int r32, int hi) {
; #pragma unroll
;   for (int r = 0; r < 16; ++r) { p0[r] = init; p1[r] = init; }
; #pragma unroll
;   for (int s = 0; s < 2; ++s) { const int c0 = s * 4 + hi * 2;
;     const v8i32 a0 = cat8(*reinterpret_cast<const v4i32*>(Kn + KN8SW(r32, c0)), *reinterpret_cast<const v4i32*>(Kn + KN8SW(r32, c0 + 1)));
;     const v8i32 a1 = cat8(*reinterpret_cast<const v4i32*>(Kn + 4096 + KN8SW(r32, c0)), *reinterpret_cast<const v4i32*>(Kn + 4096 + KN8SW(r32, c0 + 1)));
;     p0 = __builtin_amdgcn_mfma_scale_f32_32x32x64_f8f6f4(a0, qf[s], p0, 0, 0, 0, 127, 0, 124);
;     p1 = __builtin_amdgcn_mfma_scale_f32_32x32x64_f8f6f4(a1, qf[s], p1, 0, 0, 0, 127, 0, 124); }
;   { const int c0 = hi * 2;
.Lmla_s5_cont:
	s_add_i32 s30, s30, 1
	s_cmpk_lt_u32 s30, 42
	s_cbranch_scc1 .Lmla_stag_loop
	ds_read_b128 v[114:117], v215 offset:24576
	ds_read_b128 v[118:121], v216 offset:24576
	ds_read_b128 v[222:225], v215 offset:28672
	ds_read_b128 v[226:229], v216 offset:28672
	v_exp_f32_e32 v0, v82
	v_exp_f32_e32 v177, v83
	v_exp_f32_e32 v179, v84
	v_exp_f32_e32 v254, v85
	v_add_f32_e32 v219, v0, v177
	v_cvt_pk_fp8_f32 v246, v0, v177
	v_add_f32_e32 v219, v179, v219
	v_add_f32_e32 v219, v254, v219
	v_cvt_pk_fp8_f32 v246, v179, v254 op_sel:[0,0,1]
	s_waitcnt lgkmcnt(2)
	v_mfma_scale_f32_32x32x64_f8f6f4 v[114:129], v[114:121], v[146:153], v[230:245], v194, v193 op_sel_hi:[0,0,0]
	v_exp_f32_e32 v0, v86
	v_exp_f32_e32 v177, v87
	v_exp_f32_e32 v179, v88
	v_exp_f32_e32 v254, v89
	v_add_f32_e32 v219, v0, v219
	v_add_f32_e32 v219, v177, v219
	v_cvt_pk_fp8_f32 v247, v0, v177
	v_add_f32_e32 v219, v179, v219
	v_add_f32_e32 v219, v254, v219
	v_cvt_pk_fp8_f32 v247, v179, v254 op_sel:[0,0,1]
	ds_read_b128 v[82:85], v213 offset:24576
	ds_read_b128 v[86:89], v214 offset:24576
	s_waitcnt lgkmcnt(2)
	v_mfma_scale_f32_32x32x64_f8f6f4 v[98:113], v[222:229], v[146:153], v[230:245], v194, v193 op_sel_hi:[0,0,0]
	ds_read_b128 v[222:225], v213 offset:28672
	ds_read_b128 v[226:229], v214 offset:28672
	v_exp_f32_e32 v0, v90
	v_exp_f32_e32 v177, v91
	v_exp_f32_e32 v179, v92
	v_exp_f32_e32 v254, v93
	v_add_f32_e32 v219, v0, v219
	v_add_f32_e32 v219, v177, v219
	v_cvt_pk_fp8_f32 v248, v0, v177
	v_add_f32_e32 v219, v179, v219
	v_add_f32_e32 v219, v254, v219
	v_cvt_pk_fp8_f32 v248, v179, v254 op_sel:[0,0,1]
	v_exp_f32_e32 v0, v94
	v_exp_f32_e32 v177, v95
	v_exp_f32_e32 v179, v96
	v_exp_f32_e32 v254, v97
	v_add_f32_e32 v219, v0, v219
	v_add_f32_e32 v219, v177, v219
	v_cvt_pk_fp8_f32 v249, v0, v177
	v_add_f32_e32 v219, v179, v219
	v_add_f32_e32 v219, v254, v219
	v_cvt_pk_fp8_f32 v249, v179, v254 op_sel:[0,0,1]
	ds_read_b128 v[90:93], v185 offset:36864
	ds_read_b128 v[94:97], v186 offset:36864
	s_waitcnt lgkmcnt(4)
	v_mfma_scale_f32_32x32x64_f8f6f4 v[114:129], v[82:89], v[138:145], v[114:129], v194, v193 op_sel_hi:[0,0,0]
	v_exp_f32_e32 v0, v66
	v_exp_f32_e32 v177, v67
	v_exp_f32_e32 v179, v68
	v_exp_f32_e32 v254, v69
	v_add_f32_e32 v219, v0, v219
	v_add_f32_e32 v219, v177, v219
	v_cvt_pk_fp8_f32 v250, v0, v177
	v_add_f32_e32 v219, v179, v219
	v_add_f32_e32 v219, v254, v219
	v_cvt_pk_fp8_f32 v250, v179, v254 op_sel:[0,0,1]
	s_waitcnt lgkmcnt(2)
	v_mfma_scale_f32_32x32x64_f8f6f4 v[98:113], v[222:229], v[138:145], v[98:113], v194, v193 op_sel_hi:[0,0,0]
	ds_read_b128 v[222:225], v185 offset:38912
	ds_read_b128 v[226:229], v186 offset:38912
	v_exp_f32_e32 v0, v70
	v_exp_f32_e32 v177, v71
	v_exp_f32_e32 v179, v72
	v_exp_f32_e32 v254, v73
	v_add_f32_e32 v219, v0, v219
	v_add_f32_e32 v219, v177, v219
	v_cvt_pk_fp8_f32 v251, v0, v177
	v_add_f32_e32 v219, v179, v219
	v_add_f32_e32 v219, v254, v219
	v_cvt_pk_fp8_f32 v251, v179, v254 op_sel:[0,0,1]
	v_exp_f32_e32 v0, v74
	v_exp_f32_e32 v177, v75
	v_exp_f32_e32 v179, v76
	v_exp_f32_e32 v254, v77
	v_add_f32_e32 v219, v0, v219
	v_add_f32_e32 v219, v177, v219
	v_cvt_pk_fp8_f32 v252, v0, v177
	v_add_f32_e32 v219, v179, v219
	v_add_f32_e32 v219, v254, v219
	v_cvt_pk_fp8_f32 v252, v179, v254 op_sel:[0,0,1]
	s_waitcnt lgkmcnt(2)
	v_mfma_scale_f32_32x32x64_f8f6f4 v[114:129], v[90:97], v[130:137], v[114:129], v194, v193 op_sel_hi:[0,0,0]
	v_exp_f32_e32 v0, v78
	v_exp_f32_e32 v177, v79
	v_exp_f32_e32 v179, v80
	v_exp_f32_e32 v254, v81
	v_add_f32_e32 v219, v0, v219
	v_add_f32_e32 v219, v177, v219
	v_cvt_pk_fp8_f32 v253, v0, v177
	v_add_f32_e32 v219, v179, v219
	v_add_f32_e32 v219, v254, v219
	v_cvt_pk_fp8_f32 v253, v179, v254 op_sel:[0,0,1]
	ds_read_b128 v[90:93], v185 offset:0
	ds_read_b128 v[94:97], v186 offset:0
	ds_read_b128 v[82:85], v185 offset:2048
	ds_read_b128 v[86:89], v186 offset:2048
	ds_read_b128 v[74:77], v185 offset:4096
	ds_read_b128 v[78:81], v186 offset:4096
	ds_read_b128 v[66:69], v185 offset:6144
	ds_read_b128 v[70:73], v186 offset:6144
	s_waitcnt lgkmcnt(8)
	v_mfma_scale_f32_32x32x64_f8f6f4 v[98:113], v[222:229], v[130:137], v[98:113], v194, v193 op_sel_hi:[0,0,0]
	v_mov_b32_e32 v0, v219
	s_nop 1
	v_permlane32_swap_b32_e32 v219, v0
	v_add_f32_e32 v219, v219, v0
	v_fma_f32 v209, v209, v218, v219
	v_max_f32_e32 v177, v114, v115
	v_max3_f32 v177, v177, v116, v117
	v_max3_f32 v177, v177, v118, v119
	v_max3_f32 v177, v177, v120, v121
	v_max3_f32 v177, v177, v122, v123
	v_max3_f32 v177, v177, v124, v125
	v_max3_f32 v177, v177, v126, v127
	v_max3_f32 v177, v177, v128, v129
	s_waitcnt lgkmcnt(6)
	v_mfma_scale_f32_32x32x64_f8f6f4 v[50:65], v[246:253], v[90:97], v[50:65], v194, v194 op_sel_hi:[0,0,0]
	s_waitcnt vmcnt(0)
	ds_write_b128 v210, v[158:161] offset:43008
	ds_write_b128 v211, v[162:165] offset:51200
	s_waitcnt lgkmcnt(6)
	v_mfma_scale_f32_32x32x64_f8f6f4 v[34:49], v[246:253], v[82:89], v[34:49], v194, v194 op_sel_hi:[0,0,0]
	s_waitcnt lgkmcnt(0)
	s_barrier
	v_max_f32_e32 v0, v98, v99
	v_max3_f32 v0, v0, v100, v101
	v_max3_f32 v0, v0, v102, v103
	v_max3_f32 v0, v0, v104, v105
	s_waitcnt lgkmcnt(2)
	v_mfma_scale_f32_32x32x64_f8f6f4 v[18:33], v[246:253], v[74:81], v[18:33], v194, v194 op_sel_hi:[0,0,0]
	global_load_dwordx4 v[158:161], v176, s[18:19]
	global_load_dwordx4 v[162:165], v178, s[16:17]
	v_add_u32_e32 v176, 0x2000, v176
	v_add_u32_e32 v178, 0x20000, v178
	v_max3_f32 v0, v0, v106, v107
	v_max3_f32 v0, v0, v108, v109
	v_max3_f32 v0, v0, v110, v111
	v_max3_f32 v0, v0, v112, v113
	s_waitcnt lgkmcnt(0)
	v_mfma_scale_f32_32x32x64_f8f6f4 v[2:17], v[246:253], v[66:73], v[2:17], v194, v194 op_sel_hi:[0,0,0]
	v_max_f32_e32 v177, v177, v0
	v_mov_b32_e32 v0, v177
	v_mov_b32_e32 v221, 1.0
	s_nop 0
	v_permlane32_swap_b32_e32 v177, v0
	v_max_f32_e32 v177, v177, v0
	v_cmp_ge_f32_e32 vcc, s90, v177
	s_cmp_eq_u64 vcc, exec
	s_cbranch_scc0 .Lmla_q0_newmax
